# 4-slot ring k-loops with fragment reads issued as two bursts (6 A reads, then 4 B reads)
# speedup vs baseline: 1.0085x; 1.0060x over previous
.Lk_ffo:
	s_waitcnt lgkmcnt(0)
	v_mfma_f32_16x16x32_bf16 v[92:95], v[166:169], v[134:137], v[92:95]
	s_waitcnt vmcnt(10)
	s_barrier
	v_mfma_f32_16x16x32_bf16 v[88:91], v[200:203], v[134:137], v[88:91]
	s_cmp_eq_u32 s35, 0xf000
	s_cselect_b32 s38, s37, s36
	s_add_u32 s39, s34, s35
	v_mfma_f32_16x16x32_bf16 v[84:87], v[204:207], v[134:137], v[84:87]
	v_add_u32_e32 v170, s38, v170
	v_add_u32_e32 v172, s38, v172
	s_add_u32 s35, s35, s38
	v_mfma_f32_16x16x32_bf16 v[80:83], v[208:211], v[134:137], v[80:83]
	ds_read_b128 v[212:215], v170
	ds_read_b128 v[216:219], v170 offset:1024
	ds_read_b128 v[220:223], v170 offset:2048
	ds_read_b128 v[224:227], v170 offset:3072
	ds_read_b128 v[228:231], v170 offset:4096
	ds_read_b128 v[232:235], v170 offset:5120
	v_mfma_f32_16x16x32_bf16 v[76:79], v[166:169], v[138:141], v[76:79]
	v_mfma_f32_16x16x32_bf16 v[72:75], v[200:203], v[138:141], v[72:75]
	v_mfma_f32_16x16x32_bf16 v[68:71], v[204:207], v[138:141], v[68:71]
	ds_read_b128 v[244:247], v172 offset:12288
	ds_read_b128 v[248:251], v172 offset:13312
	ds_read_b128 v[252:255], v172 offset:14336
	ds_read_b128 v[116:119], v172 offset:15360
	v_mfma_f32_16x16x32_bf16 v[64:67], v[208:211], v[138:141], v[64:67]
	v_mfma_f32_16x16x32_bf16 v[60:63], v[166:169], v[150:153], v[60:63]
	s_mov_b32 m0, s39
	v_mfma_f32_16x16x32_bf16 v[56:59], v[200:203], v[150:153], v[56:59]
	global_load_lds_dwordx4 v[124:125], off
	v_lshl_add_u64 v[124:125], v[124:125], 0, 64
	v_mfma_f32_16x16x32_bf16 v[52:55], v[204:207], v[150:153], v[52:55]
	s_add_u32 m0, s39, 0x1000
	v_mfma_f32_16x16x32_bf16 v[48:51], v[208:211], v[150:153], v[48:51]
	global_load_lds_dwordx4 v[122:123], off
	v_lshl_add_u64 v[122:123], v[122:123], 0, 64
	v_mfma_f32_16x16x32_bf16 v[44:47], v[166:169], v[154:157], v[44:47]
	s_add_u32 m0, s39, 0x2000
	v_mfma_f32_16x16x32_bf16 v[40:43], v[200:203], v[154:157], v[40:43]
	global_load_lds_dwordx4 v[120:121], off
	v_lshl_add_u64 v[120:121], v[120:121], 0, 64
	v_mfma_f32_16x16x32_bf16 v[36:39], v[204:207], v[154:157], v[36:39]
	s_add_u32 m0, s39, 0x3000
	v_mfma_f32_16x16x32_bf16 v[32:35], v[208:211], v[154:157], v[32:35]
	global_load_lds_dwordx4 v[236:237], off
	v_lshl_add_u64 v[236:237], v[236:237], 0, 64
	v_mfma_f32_16x16x32_bf16 v[28:31], v[166:169], v[158:161], v[28:31]
	s_add_u32 m0, s39, 0x4000
	v_mfma_f32_16x16x32_bf16 v[24:27], v[200:203], v[158:161], v[24:27]
	global_load_lds_dwordx4 v[126:127], off
	v_lshl_add_u64 v[126:127], v[126:127], 0, 64
	v_mfma_f32_16x16x32_bf16 v[20:23], v[204:207], v[158:161], v[20:23]
	v_mfma_f32_16x16x32_bf16 v[16:19], v[208:211], v[158:161], v[16:19]
	v_mfma_f32_16x16x32_bf16 v[8:11], v[166:169], v[162:165], v[8:11]
	v_mfma_f32_16x16x32_bf16 v[4:7], v[200:203], v[162:165], v[4:7]
	v_mfma_f32_16x16x32_bf16 v[12:15], v[204:207], v[162:165], v[12:15]
	v_mfma_f32_16x16x32_bf16 v[0:3], v[208:211], v[162:165], v[0:3]
	s_waitcnt lgkmcnt(0)
	v_mfma_f32_16x16x32_bf16 v[92:95], v[244:247], v[212:215], v[92:95]
	s_waitcnt vmcnt(10)
	s_barrier
	v_mfma_f32_16x16x32_bf16 v[88:91], v[248:251], v[212:215], v[88:91]
	s_cmp_eq_u32 s35, 0xf000
	s_cselect_b32 s38, s37, s36
	s_add_u32 s39, s34, s35
	v_mfma_f32_16x16x32_bf16 v[84:87], v[252:255], v[212:215], v[84:87]
	v_add_u32_e32 v170, s38, v170
	v_add_u32_e32 v172, s38, v172
	s_add_u32 s35, s35, s38
	v_mfma_f32_16x16x32_bf16 v[80:83], v[116:119], v[212:215], v[80:83]
	ds_read_b128 v[134:137], v170
	ds_read_b128 v[138:141], v170 offset:1024
	ds_read_b128 v[150:153], v170 offset:2048
	ds_read_b128 v[154:157], v170 offset:3072
	ds_read_b128 v[158:161], v170 offset:4096
	ds_read_b128 v[162:165], v170 offset:5120
	v_mfma_f32_16x16x32_bf16 v[76:79], v[244:247], v[216:219], v[76:79]
	v_mfma_f32_16x16x32_bf16 v[72:75], v[248:251], v[216:219], v[72:75]
	v_mfma_f32_16x16x32_bf16 v[68:71], v[252:255], v[216:219], v[68:71]
	ds_read_b128 v[166:169], v172 offset:12288
	ds_read_b128 v[200:203], v172 offset:13312
	ds_read_b128 v[204:207], v172 offset:14336
	ds_read_b128 v[208:211], v172 offset:15360
	v_mfma_f32_16x16x32_bf16 v[64:67], v[116:119], v[216:219], v[64:67]
	v_mfma_f32_16x16x32_bf16 v[60:63], v[244:247], v[220:223], v[60:63]
	s_mov_b32 m0, s39
	v_mfma_f32_16x16x32_bf16 v[56:59], v[248:251], v[220:223], v[56:59]
	global_load_lds_dwordx4 v[124:125], off
	v_lshl_add_u64 v[124:125], v[124:125], 0, 64
	v_mfma_f32_16x16x32_bf16 v[52:55], v[252:255], v[220:223], v[52:55]
	s_add_u32 m0, s39, 0x1000
	v_mfma_f32_16x16x32_bf16 v[48:51], v[116:119], v[220:223], v[48:51]
	global_load_lds_dwordx4 v[122:123], off
	v_lshl_add_u64 v[122:123], v[122:123], 0, 64
	v_mfma_f32_16x16x32_bf16 v[44:47], v[244:247], v[224:227], v[44:47]
	s_add_u32 m0, s39, 0x2000
	v_mfma_f32_16x16x32_bf16 v[40:43], v[248:251], v[224:227], v[40:43]
	global_load_lds_dwordx4 v[120:121], off
	v_lshl_add_u64 v[120:121], v[120:121], 0, 64
	v_mfma_f32_16x16x32_bf16 v[36:39], v[252:255], v[224:227], v[36:39]
	s_add_u32 m0, s39, 0x3000
	v_mfma_f32_16x16x32_bf16 v[32:35], v[116:119], v[224:227], v[32:35]
	global_load_lds_dwordx4 v[236:237], off
	v_lshl_add_u64 v[236:237], v[236:237], 0, 64
	v_mfma_f32_16x16x32_bf16 v[28:31], v[244:247], v[228:231], v[28:31]
	s_add_u32 m0, s39, 0x4000
	v_mfma_f32_16x16x32_bf16 v[24:27], v[248:251], v[228:231], v[24:27]
	global_load_lds_dwordx4 v[126:127], off
	v_lshl_add_u64 v[126:127], v[126:127], 0, 64
	v_mfma_f32_16x16x32_bf16 v[20:23], v[252:255], v[228:231], v[20:23]
	s_add_i32 s41, s41, -1
	s_cmp_eq_u32 s41, 0
	v_mfma_f32_16x16x32_bf16 v[16:19], v[116:119], v[228:231], v[16:19]
	v_mfma_f32_16x16x32_bf16 v[8:11], v[244:247], v[232:235], v[8:11]
	v_mfma_f32_16x16x32_bf16 v[4:7], v[248:251], v[232:235], v[4:7]
	v_mfma_f32_16x16x32_bf16 v[12:15], v[252:255], v[232:235], v[12:15]
	v_mfma_f32_16x16x32_bf16 v[0:3], v[116:119], v[232:235], v[0:3]
	s_cbranch_scc0 .Lk_ffo
	s_waitcnt lgkmcnt(0)
	v_mfma_f32_16x16x32_bf16 v[92:95], v[166:169], v[134:137], v[92:95]
	s_waitcnt vmcnt(10)
	s_barrier
	v_mfma_f32_16x16x32_bf16 v[88:91], v[200:203], v[134:137], v[88:91]
	s_cmp_eq_u32 s35, 0xf000
	s_cselect_b32 s38, s37, s36
	v_mfma_f32_16x16x32_bf16 v[84:87], v[204:207], v[134:137], v[84:87]
	v_add_u32_e32 v170, s38, v170
	v_add_u32_e32 v172, s38, v172
	s_add_u32 s35, s35, s38
	v_mfma_f32_16x16x32_bf16 v[80:83], v[208:211], v[134:137], v[80:83]
	ds_read_b128 v[212:215], v170
	ds_read_b128 v[216:219], v170 offset:1024
	ds_read_b128 v[220:223], v170 offset:2048
	ds_read_b128 v[224:227], v170 offset:3072
	ds_read_b128 v[228:231], v170 offset:4096
	ds_read_b128 v[232:235], v170 offset:5120
	v_mfma_f32_16x16x32_bf16 v[76:79], v[166:169], v[138:141], v[76:79]
	v_mfma_f32_16x16x32_bf16 v[72:75], v[200:203], v[138:141], v[72:75]
	v_mfma_f32_16x16x32_bf16 v[68:71], v[204:207], v[138:141], v[68:71]
	ds_read_b128 v[244:247], v172 offset:12288
	ds_read_b128 v[248:251], v172 offset:13312
	ds_read_b128 v[252:255], v172 offset:14336
	ds_read_b128 v[116:119], v172 offset:15360
	v_mfma_f32_16x16x32_bf16 v[64:67], v[208:211], v[138:141], v[64:67]
	v_mfma_f32_16x16x32_bf16 v[60:63], v[166:169], v[150:153], v[60:63]
	v_mfma_f32_16x16x32_bf16 v[56:59], v[200:203], v[150:153], v[56:59]
	v_mfma_f32_16x16x32_bf16 v[52:55], v[204:207], v[150:153], v[52:55]
	v_mfma_f32_16x16x32_bf16 v[48:51], v[208:211], v[150:153], v[48:51]
	v_mfma_f32_16x16x32_bf16 v[44:47], v[166:169], v[154:157], v[44:47]
	v_mfma_f32_16x16x32_bf16 v[40:43], v[200:203], v[154:157], v[40:43]
	v_mfma_f32_16x16x32_bf16 v[36:39], v[204:207], v[154:157], v[36:39]
	v_mfma_f32_16x16x32_bf16 v[32:35], v[208:211], v[154:157], v[32:35]
	v_mfma_f32_16x16x32_bf16 v[28:31], v[166:169], v[158:161], v[28:31]
	v_mfma_f32_16x16x32_bf16 v[24:27], v[200:203], v[158:161], v[24:27]
	v_mfma_f32_16x16x32_bf16 v[20:23], v[204:207], v[158:161], v[20:23]
	v_mfma_f32_16x16x32_bf16 v[16:19], v[208:211], v[158:161], v[16:19]
	v_mfma_f32_16x16x32_bf16 v[8:11], v[166:169], v[162:165], v[8:11]
	v_mfma_f32_16x16x32_bf16 v[4:7], v[200:203], v[162:165], v[4:7]
	v_mfma_f32_16x16x32_bf16 v[12:15], v[204:207], v[162:165], v[12:15]
	v_mfma_f32_16x16x32_bf16 v[0:3], v[208:211], v[162:165], v[0:3]
	s_waitcnt lgkmcnt(0)
	v_mfma_f32_16x16x32_bf16 v[92:95], v[244:247], v[212:215], v[92:95]
	s_waitcnt vmcnt(5)
	s_barrier
	v_mfma_f32_16x16x32_bf16 v[88:91], v[248:251], v[212:215], v[88:91]
	s_cmp_eq_u32 s35, 0xf000
	s_cselect_b32 s38, s37, s36
	v_mfma_f32_16x16x32_bf16 v[84:87], v[252:255], v[212:215], v[84:87]
	v_add_u32_e32 v170, s38, v170
	v_add_u32_e32 v172, s38, v172
	s_add_u32 s35, s35, s38
	v_mfma_f32_16x16x32_bf16 v[80:83], v[116:119], v[212:215], v[80:83]
	ds_read_b128 v[134:137], v170
	ds_read_b128 v[138:141], v170 offset:1024
	ds_read_b128 v[150:153], v170 offset:2048
	ds_read_b128 v[154:157], v170 offset:3072
	ds_read_b128 v[158:161], v170 offset:4096
	ds_read_b128 v[162:165], v170 offset:5120
	v_mfma_f32_16x16x32_bf16 v[76:79], v[244:247], v[216:219], v[76:79]
	v_mfma_f32_16x16x32_bf16 v[72:75], v[248:251], v[216:219], v[72:75]
	v_mfma_f32_16x16x32_bf16 v[68:71], v[252:255], v[216:219], v[68:71]
	ds_read_b128 v[166:169], v172 offset:12288
	ds_read_b128 v[200:203], v172 offset:13312
	ds_read_b128 v[204:207], v172 offset:14336
	ds_read_b128 v[208:211], v172 offset:15360
	v_mfma_f32_16x16x32_bf16 v[64:67], v[116:119], v[216:219], v[64:67]
	v_mfma_f32_16x16x32_bf16 v[60:63], v[244:247], v[220:223], v[60:63]
	v_mfma_f32_16x16x32_bf16 v[56:59], v[248:251], v[220:223], v[56:59]
	v_mfma_f32_16x16x32_bf16 v[52:55], v[252:255], v[220:223], v[52:55]
	v_mfma_f32_16x16x32_bf16 v[48:51], v[116:119], v[220:223], v[48:51]
	v_mfma_f32_16x16x32_bf16 v[44:47], v[244:247], v[224:227], v[44:47]
	v_mfma_f32_16x16x32_bf16 v[40:43], v[248:251], v[224:227], v[40:43]
	v_mfma_f32_16x16x32_bf16 v[36:39], v[252:255], v[224:227], v[36:39]
	v_mfma_f32_16x16x32_bf16 v[32:35], v[116:119], v[224:227], v[32:35]
	v_mfma_f32_16x16x32_bf16 v[28:31], v[244:247], v[228:231], v[28:31]
	v_mfma_f32_16x16x32_bf16 v[24:27], v[248:251], v[228:231], v[24:27]
	v_mfma_f32_16x16x32_bf16 v[20:23], v[252:255], v[228:231], v[20:23]
	v_mfma_f32_16x16x32_bf16 v[16:19], v[116:119], v[228:231], v[16:19]
	v_mfma_f32_16x16x32_bf16 v[8:11], v[244:247], v[232:235], v[8:11]
	v_mfma_f32_16x16x32_bf16 v[4:7], v[248:251], v[232:235], v[4:7]
	v_mfma_f32_16x16x32_bf16 v[12:15], v[252:255], v[232:235], v[12:15]
	v_mfma_f32_16x16x32_bf16 v[0:3], v[116:119], v[232:235], v[0:3]
	s_waitcnt lgkmcnt(0)
	v_mfma_f32_16x16x32_bf16 v[92:95], v[166:169], v[134:137], v[92:95]
	s_waitcnt vmcnt(0)
	s_barrier
	v_mfma_f32_16x16x32_bf16 v[88:91], v[200:203], v[134:137], v[88:91]
	s_cmp_eq_u32 s35, 0xf000
	s_cselect_b32 s38, s37, s36
	v_mfma_f32_16x16x32_bf16 v[84:87], v[204:207], v[134:137], v[84:87]
	v_add_u32_e32 v170, s38, v170
	v_add_u32_e32 v172, s38, v172
	s_add_u32 s35, s35, s38
	v_mfma_f32_16x16x32_bf16 v[80:83], v[208:211], v[134:137], v[80:83]
	ds_read_b128 v[212:215], v170
	ds_read_b128 v[216:219], v170 offset:1024
	ds_read_b128 v[220:223], v170 offset:2048
	ds_read_b128 v[224:227], v170 offset:3072
	ds_read_b128 v[228:231], v170 offset:4096
	ds_read_b128 v[232:235], v170 offset:5120
	v_mfma_f32_16x16x32_bf16 v[76:79], v[166:169], v[138:141], v[76:79]
	v_mfma_f32_16x16x32_bf16 v[72:75], v[200:203], v[138:141], v[72:75]
	v_mfma_f32_16x16x32_bf16 v[68:71], v[204:207], v[138:141], v[68:71]
	ds_read_b128 v[244:247], v172 offset:12288
	ds_read_b128 v[248:251], v172 offset:13312
	ds_read_b128 v[252:255], v172 offset:14336
	ds_read_b128 v[116:119], v172 offset:15360
	v_mfma_f32_16x16x32_bf16 v[64:67], v[208:211], v[138:141], v[64:67]
	v_mfma_f32_16x16x32_bf16 v[60:63], v[166:169], v[150:153], v[60:63]
	v_mfma_f32_16x16x32_bf16 v[56:59], v[200:203], v[150:153], v[56:59]
	v_mfma_f32_16x16x32_bf16 v[52:55], v[204:207], v[150:153], v[52:55]
	v_mfma_f32_16x16x32_bf16 v[48:51], v[208:211], v[150:153], v[48:51]
	v_mfma_f32_16x16x32_bf16 v[44:47], v[166:169], v[154:157], v[44:47]
	v_mfma_f32_16x16x32_bf16 v[40:43], v[200:203], v[154:157], v[40:43]
	v_mfma_f32_16x16x32_bf16 v[36:39], v[204:207], v[154:157], v[36:39]
	v_mfma_f32_16x16x32_bf16 v[32:35], v[208:211], v[154:157], v[32:35]
	v_mfma_f32_16x16x32_bf16 v[28:31], v[166:169], v[158:161], v[28:31]
	v_mfma_f32_16x16x32_bf16 v[24:27], v[200:203], v[158:161], v[24:27]
	v_mfma_f32_16x16x32_bf16 v[20:23], v[204:207], v[158:161], v[20:23]
	v_mfma_f32_16x16x32_bf16 v[16:19], v[208:211], v[158:161], v[16:19]
	v_mfma_f32_16x16x32_bf16 v[8:11], v[166:169], v[162:165], v[8:11]
	v_mfma_f32_16x16x32_bf16 v[4:7], v[200:203], v[162:165], v[4:7]
	v_mfma_f32_16x16x32_bf16 v[12:15], v[204:207], v[162:165], v[12:15]
	v_mfma_f32_16x16x32_bf16 v[0:3], v[208:211], v[162:165], v[0:3]
	s_waitcnt lgkmcnt(0)
	v_mfma_f32_16x16x32_bf16 v[92:95], v[244:247], v[212:215], v[92:95]
	v_mfma_f32_16x16x32_bf16 v[88:91], v[248:251], v[212:215], v[88:91]
	v_mfma_f32_16x16x32_bf16 v[84:87], v[252:255], v[212:215], v[84:87]
	v_mfma_f32_16x16x32_bf16 v[80:83], v[116:119], v[212:215], v[80:83]
	v_mfma_f32_16x16x32_bf16 v[76:79], v[244:247], v[216:219], v[76:79]
	v_mfma_f32_16x16x32_bf16 v[72:75], v[248:251], v[216:219], v[72:75]
	v_mfma_f32_16x16x32_bf16 v[68:71], v[252:255], v[216:219], v[68:71]
	v_mfma_f32_16x16x32_bf16 v[64:67], v[116:119], v[216:219], v[64:67]
	v_mfma_f32_16x16x32_bf16 v[60:63], v[244:247], v[220:223], v[60:63]
	v_mfma_f32_16x16x32_bf16 v[56:59], v[248:251], v[220:223], v[56:59]
	v_mfma_f32_16x16x32_bf16 v[52:55], v[252:255], v[220:223], v[52:55]
	v_mfma_f32_16x16x32_bf16 v[48:51], v[116:119], v[220:223], v[48:51]
	v_mfma_f32_16x16x32_bf16 v[44:47], v[244:247], v[224:227], v[44:47]
	v_mfma_f32_16x16x32_bf16 v[40:43], v[248:251], v[224:227], v[40:43]
	v_mfma_f32_16x16x32_bf16 v[36:39], v[252:255], v[224:227], v[36:39]
	v_mfma_f32_16x16x32_bf16 v[32:35], v[116:119], v[224:227], v[32:35]
	v_mfma_f32_16x16x32_bf16 v[28:31], v[244:247], v[228:231], v[28:31]
	v_mfma_f32_16x16x32_bf16 v[24:27], v[248:251], v[228:231], v[24:27]
	v_mfma_f32_16x16x32_bf16 v[20:23], v[252:255], v[228:231], v[20:23]
	v_mfma_f32_16x16x32_bf16 v[16:19], v[116:119], v[228:231], v[16:19]
	v_mfma_f32_16x16x32_bf16 v[8:11], v[244:247], v[232:235], v[8:11]
	v_mfma_f32_16x16x32_bf16 v[4:7], v[248:251], v[232:235], v[4:7]
	v_mfma_f32_16x16x32_bf16 v[12:15], v[252:255], v[232:235], v[12:15]
	v_mfma_f32_16x16x32_bf16 v[0:3], v[116:119], v[232:235], v[0:3]
	s_barrier
	v_mov_b32_e32 v170, s46
	v_mov_b32_e32 v172, s47
	ds_write_b32 v183, v170
	ds_write_b32 v184, v172
	s_waitcnt lgkmcnt(0)
	s_mulk_i32 s7, 0xc0
	s_add_i32 s5, s5, s51
	v_readlane_b32 s10, v242, 27
	v_readlane_b32 s11, v242, 28
	v_readlane_b32 s12, v242, 25
	v_readlane_b32 s13, v242, 26
	v_readlane_b32 s14, v243, 11
	v_readlane_b32 s15, v243, 12
	s_mov_b32 s8, 0x3fd744fd
	v_add_u32_e32 v236, s7, v145
	v_or_b32_e32 v254, s6, v146
	v_mov_b32_e32 v255, 0
	v_or_b32_e32 v237, v236, v133
	v_lshlrev_b64 v[254:255], 2, v[254:255]
	s_nop 0
	v_lshl_add_u64 v[250:251], s[12:13], 0, v[254:255]
	v_lshl_add_u64 v[252:253], s[14:15], 0, v[254:255]
	s_mov_b64 s[14:15], 0x5000
	v_lshl_add_u64 v[252:253], v[252:253], 0, s[14:15]
	v_readlane_b32 s12, v242, 29
	v_readlane_b32 s13, v242, 30
	v_lshl_add_u64 v[248:249], s[12:13], 0, v[254:255]
	v_readlane_b32 s12, v241, 9
	s_add_i32 s12, s12, -10
	s_mul_i32 s12, s12, 57
	s_lshr_b32 s12, s12, 9
	s_lshl_b32 s12, s12, 12
	v_readlane_b32 s14, v243, 59
	v_readlane_b32 s15, v243, 60
	s_add_u32 s14, s14, s12
	s_addc_u32 s15, s15, 0
	v_lshl_add_u64 v[224:225], s[14:15], 0, v[254:255]
	v_readlane_b32 s14, v243, 61
	v_readlane_b32 s15, v243, 62
	s_add_u32 s14, s14, s12
	s_addc_u32 s15, s15, 0
	v_lshl_add_u64 v[226:227], s[14:15], 0, v[254:255]
	global_load_dwordx4 v[96:99], v[224:225], off
	global_load_dwordx4 v[112:115], v[226:227], off
	global_load_dwordx4 v[100:103], v[224:225], off offset:64
	global_load_dwordx4 v[150:153], v[226:227], off offset:64
	global_load_dwordx4 v[104:107], v[224:225], off offset:128
	global_load_dwordx4 v[142:145], v[226:227], off offset:128
	global_load_dwordx4 v[108:111], v[224:225], off offset:192
	global_load_dwordx4 v[146:149], v[226:227], off offset:192
	v_mov_b32_e32 v255, 0
	v_add_u32_e32 v254, 0, v237
	v_add_u32_e32 v236, 0xfffff000, v254
	v_cmp_lt_i32_e32 vcc, 0xfff, v254
	v_lshrrev_b32_e32 v236, 10, v236
	v_lshlrev_b32_e32 v224, 3, v254
	v_lshlrev_b32_e32 v254, 12, v254
	v_add_u32_e32 v236, 1, v236
	v_mov_b32_e32 v225, 0
	v_cndmask_b32_e32 v236, 0, v236, vcc
	v_lshl_add_u64 v[224:225], v[224:225], 0, s[10:11]
	v_lshl_add_u64 v[228:229], v[254:255], 0, v[250:251]
	v_add_u32_e32 v236, s4, v236
	v_mad_i64_i32 v[232:233], s[0:1], v236, s33, v[252:253]
	global_load_dwordx2 v[132:133], v[224:225], off
	v_lshl_add_u64 v[224:225], v[254:255], 0, v[248:249]
	v_add_u32_e32 v254, 16, v237
	v_add_u32_e32 v236, 0xfffff000, v254
	v_cmp_lt_i32_e32 vcc, 0xfff, v254
	v_lshrrev_b32_e32 v236, 10, v236
	v_lshlrev_b32_e32 v226, 3, v254
	v_lshlrev_b32_e32 v254, 12, v254
	v_add_u32_e32 v236, 1, v236
	v_mov_b32_e32 v227, 0
	v_cndmask_b32_e32 v236, 0, v236, vcc
	v_lshl_add_u64 v[226:227], v[226:227], 0, s[10:11]
	v_lshl_add_u64 v[230:231], v[254:255], 0, v[250:251]
	v_add_u32_e32 v236, s4, v236
	v_mad_i64_i32 v[234:235], s[0:1], v236, s33, v[252:253]
	global_load_dword v128, v[226:227], off
	global_load_dword v170, v[226:227], off offset:4
	v_lshl_add_u64 v[226:227], v[254:255], 0, v[248:249]
	global_load_dwordx4 v[154:157], v[224:225], off
	global_load_dwordx4 v[116:119], v[232:233], off
	global_load_dwordx4 v[158:161], v[224:225], off offset:64
	global_load_dwordx4 v[120:123], v[232:233], off offset:64
	global_load_dwordx4 v[162:165], v[224:225], off offset:128
	global_load_dwordx4 v[124:127], v[232:233], off offset:128
	global_load_dwordx4 v[166:169], v[224:225], off offset:192
	global_load_dwordx4 v[134:137], v[232:233], off offset:192
	global_load_dwordx4 v[208:211], v[226:227], off
	global_load_dwordx4 v[138:141], v[234:235], off
	global_load_dwordx4 v[212:215], v[226:227], off offset:64
	global_load_dwordx4 v[200:203], v[234:235], off offset:64
	global_load_dwordx4 v[216:219], v[226:227], off offset:128
	global_load_dwordx4 v[204:207], v[234:235], off offset:128
	global_load_dwordx4 v[220:223], v[226:227], off offset:192
	global_load_dwordx4 v[244:247], v[234:235], off offset:192
	s_waitcnt vmcnt(0)
	v_pk_mul_f32 v[92:93], v[92:93], v[116:117]
	v_pk_add_f32 v[154:155], v[154:155], v[132:133] op_sel_hi:[1,0] neg_lo:[0,1] neg_hi:[0,1]
	v_pk_mul_f32 v[94:95], v[94:95], v[118:119]
	v_pk_add_f32 v[156:157], v[156:157], v[132:133] op_sel_hi:[1,0] neg_lo:[0,1] neg_hi:[0,1]
	v_pk_mul_f32 v[154:155], v[154:155], v[132:133] op_sel:[0,1] op_sel_hi:[1,1]
	v_pk_mul_f32 v[156:157], v[156:157], v[132:133] op_sel:[0,1] op_sel_hi:[1,1]
	v_pk_fma_f32 v[154:155], v[96:97], v[154:155], v[112:113]
	v_pk_fma_f32 v[156:157], v[98:99], v[156:157], v[114:115]
	v_pk_fma_f32 v[92:93], v[154:155], s[8:9], v[92:93] op_sel_hi:[1,0,1]
	v_pk_fma_f32 v[94:95], v[156:157], s[8:9], v[94:95] op_sel_hi:[1,0,1]
	global_store_dwordx4 v[228:229], v[92:95], off
	v_pk_mul_f32 v[88:89], v[88:89], v[120:121]
	v_pk_add_f32 v[158:159], v[158:159], v[132:133] op_sel_hi:[1,0] neg_lo:[0,1] neg_hi:[0,1]
	v_pk_mul_f32 v[90:91], v[90:91], v[122:123]
	v_pk_add_f32 v[160:161], v[160:161], v[132:133] op_sel_hi:[1,0] neg_lo:[0,1] neg_hi:[0,1]
	v_pk_mul_f32 v[158:159], v[158:159], v[132:133] op_sel:[0,1] op_sel_hi:[1,1]
	v_pk_mul_f32 v[160:161], v[160:161], v[132:133] op_sel:[0,1] op_sel_hi:[1,1]
	v_pk_fma_f32 v[158:159], v[100:101], v[158:159], v[150:151]
	v_pk_fma_f32 v[160:161], v[102:103], v[160:161], v[152:153]
	v_pk_fma_f32 v[88:89], v[158:159], s[8:9], v[88:89] op_sel_hi:[1,0,1]
	v_pk_fma_f32 v[90:91], v[160:161], s[8:9], v[90:91] op_sel_hi:[1,0,1]
	global_store_dwordx4 v[228:229], v[88:91], off offset:64
	v_pk_mul_f32 v[84:85], v[84:85], v[124:125]
	v_pk_add_f32 v[162:163], v[162:163], v[132:133] op_sel_hi:[1,0] neg_lo:[0,1] neg_hi:[0,1]
	v_pk_mul_f32 v[86:87], v[86:87], v[126:127]
	v_pk_add_f32 v[164:165], v[164:165], v[132:133] op_sel_hi:[1,0] neg_lo:[0,1] neg_hi:[0,1]
	v_pk_mul_f32 v[162:163], v[162:163], v[132:133] op_sel:[0,1] op_sel_hi:[1,1]
	v_pk_mul_f32 v[164:165], v[164:165], v[132:133] op_sel:[0,1] op_sel_hi:[1,1]
	v_pk_fma_f32 v[162:163], v[104:105], v[162:163], v[142:143]
	v_pk_fma_f32 v[164:165], v[106:107], v[164:165], v[144:145]
	v_pk_fma_f32 v[84:85], v[162:163], s[8:9], v[84:85] op_sel_hi:[1,0,1]
	v_pk_fma_f32 v[86:87], v[164:165], s[8:9], v[86:87] op_sel_hi:[1,0,1]
	global_store_dwordx4 v[228:229], v[84:87], off offset:128
	v_pk_mul_f32 v[80:81], v[80:81], v[134:135]
	v_pk_add_f32 v[166:167], v[166:167], v[132:133] op_sel_hi:[1,0] neg_lo:[0,1] neg_hi:[0,1]
	v_pk_mul_f32 v[82:83], v[82:83], v[136:137]
	v_pk_add_f32 v[168:169], v[168:169], v[132:133] op_sel_hi:[1,0] neg_lo:[0,1] neg_hi:[0,1]
	v_pk_mul_f32 v[166:167], v[166:167], v[132:133] op_sel:[0,1] op_sel_hi:[1,1]
	v_pk_mul_f32 v[168:169], v[168:169], v[132:133] op_sel:[0,1] op_sel_hi:[1,1]
	v_pk_fma_f32 v[166:167], v[108:109], v[166:167], v[146:147]
	v_pk_fma_f32 v[168:169], v[110:111], v[168:169], v[148:149]
	v_pk_fma_f32 v[80:81], v[166:167], s[8:9], v[80:81] op_sel_hi:[1,0,1]
	v_pk_fma_f32 v[82:83], v[168:169], s[8:9], v[82:83] op_sel_hi:[1,0,1]
	global_store_dwordx4 v[228:229], v[80:83], off offset:192
	v_pk_mul_f32 v[76:77], v[76:77], v[138:139]
	v_pk_add_f32 v[208:209], v[208:209], v[128:129] op_sel_hi:[1,0] neg_lo:[0,1] neg_hi:[0,1]
	v_pk_mul_f32 v[78:79], v[78:79], v[140:141]
	v_pk_add_f32 v[210:211], v[210:211], v[128:129] op_sel_hi:[1,0] neg_lo:[0,1] neg_hi:[0,1]
	v_pk_mul_f32 v[208:209], v[208:209], v[170:171] op_sel_hi:[1,0]
	v_pk_mul_f32 v[210:211], v[210:211], v[170:171] op_sel_hi:[1,0]
	v_pk_fma_f32 v[208:209], v[96:97], v[208:209], v[112:113]
	v_pk_fma_f32 v[210:211], v[98:99], v[210:211], v[114:115]
	v_pk_fma_f32 v[76:77], v[208:209], s[8:9], v[76:77] op_sel_hi:[1,0,1]
	v_pk_fma_f32 v[78:79], v[210:211], s[8:9], v[78:79] op_sel_hi:[1,0,1]
	global_store_dwordx4 v[230:231], v[76:79], off
	v_pk_mul_f32 v[72:73], v[72:73], v[200:201]
	v_pk_add_f32 v[212:213], v[212:213], v[128:129] op_sel_hi:[1,0] neg_lo:[0,1] neg_hi:[0,1]
	v_pk_mul_f32 v[74:75], v[74:75], v[202:203]
	v_pk_add_f32 v[214:215], v[214:215], v[128:129] op_sel_hi:[1,0] neg_lo:[0,1] neg_hi:[0,1]
	v_pk_mul_f32 v[212:213], v[212:213], v[170:171] op_sel_hi:[1,0]
	v_pk_mul_f32 v[214:215], v[214:215], v[170:171] op_sel_hi:[1,0]
	v_pk_fma_f32 v[212:213], v[100:101], v[212:213], v[150:151]
	v_pk_fma_f32 v[214:215], v[102:103], v[214:215], v[152:153]
	v_pk_fma_f32 v[72:73], v[212:213], s[8:9], v[72:73] op_sel_hi:[1,0,1]
	v_pk_fma_f32 v[74:75], v[214:215], s[8:9], v[74:75] op_sel_hi:[1,0,1]
	global_store_dwordx4 v[230:231], v[72:75], off offset:64
	v_pk_mul_f32 v[68:69], v[68:69], v[204:205]
	v_pk_add_f32 v[216:217], v[216:217], v[128:129] op_sel_hi:[1,0] neg_lo:[0,1] neg_hi:[0,1]
	v_pk_mul_f32 v[70:71], v[70:71], v[206:207]
	v_pk_add_f32 v[218:219], v[218:219], v[128:129] op_sel_hi:[1,0] neg_lo:[0,1] neg_hi:[0,1]
	v_pk_mul_f32 v[216:217], v[216:217], v[170:171] op_sel_hi:[1,0]
	v_pk_mul_f32 v[218:219], v[218:219], v[170:171] op_sel_hi:[1,0]
	v_pk_fma_f32 v[216:217], v[104:105], v[216:217], v[142:143]
	v_pk_fma_f32 v[218:219], v[106:107], v[218:219], v[144:145]
	v_pk_fma_f32 v[68:69], v[216:217], s[8:9], v[68:69] op_sel_hi:[1,0,1]
	v_pk_fma_f32 v[70:71], v[218:219], s[8:9], v[70:71] op_sel_hi:[1,0,1]
	global_store_dwordx4 v[230:231], v[68:71], off offset:128
	v_pk_mul_f32 v[64:65], v[64:65], v[244:245]
	v_pk_add_f32 v[220:221], v[220:221], v[128:129] op_sel_hi:[1,0] neg_lo:[0,1] neg_hi:[0,1]
	v_pk_mul_f32 v[66:67], v[66:67], v[246:247]
	v_pk_add_f32 v[222:223], v[222:223], v[128:129] op_sel_hi:[1,0] neg_lo:[0,1] neg_hi:[0,1]
	v_pk_mul_f32 v[220:221], v[220:221], v[170:171] op_sel_hi:[1,0]
	v_pk_mul_f32 v[222:223], v[222:223], v[170:171] op_sel_hi:[1,0]
	v_pk_fma_f32 v[220:221], v[108:109], v[220:221], v[146:147]
	v_pk_fma_f32 v[222:223], v[110:111], v[222:223], v[148:149]
	v_pk_fma_f32 v[64:65], v[220:221], s[8:9], v[64:65] op_sel_hi:[1,0,1]
	v_pk_fma_f32 v[66:67], v[222:223], s[8:9], v[66:67] op_sel_hi:[1,0,1]
	global_store_dwordx4 v[230:231], v[64:67], off offset:192
	v_add_u32_e32 v254, 32, v237
	v_add_u32_e32 v236, 0xfffff000, v254
	v_cmp_lt_i32_e32 vcc, 0xfff, v254
	v_lshrrev_b32_e32 v236, 10, v236
	v_lshlrev_b32_e32 v224, 3, v254
	v_lshlrev_b32_e32 v254, 12, v254
	v_add_u32_e32 v236, 1, v236
	v_mov_b32_e32 v225, 0
	v_cndmask_b32_e32 v236, 0, v236, vcc
	v_lshl_add_u64 v[224:225], v[224:225], 0, s[10:11]
	v_lshl_add_u64 v[228:229], v[254:255], 0, v[250:251]
	v_add_u32_e32 v236, s4, v236
	v_mad_i64_i32 v[232:233], s[0:1], v236, s33, v[252:253]
	global_load_dwordx2 v[132:133], v[224:225], off
	v_lshl_add_u64 v[224:225], v[254:255], 0, v[248:249]
	v_add_u32_e32 v254, 48, v237
	v_add_u32_e32 v236, 0xfffff000, v254
	v_cmp_lt_i32_e32 vcc, 0xfff, v254
	v_lshrrev_b32_e32 v236, 10, v236
	v_lshlrev_b32_e32 v226, 3, v254
	v_lshlrev_b32_e32 v254, 12, v254
	v_add_u32_e32 v236, 1, v236
	v_mov_b32_e32 v227, 0
	v_cndmask_b32_e32 v236, 0, v236, vcc
	v_lshl_add_u64 v[226:227], v[226:227], 0, s[10:11]
	v_lshl_add_u64 v[230:231], v[254:255], 0, v[250:251]
	v_add_u32_e32 v236, s4, v236
	v_mad_i64_i32 v[234:235], s[0:1], v236, s33, v[252:253]
	global_load_dword v128, v[226:227], off
	global_load_dword v170, v[226:227], off offset:4
	v_lshl_add_u64 v[226:227], v[254:255], 0, v[248:249]
	global_load_dwordx4 v[154:157], v[224:225], off
	global_load_dwordx4 v[116:119], v[232:233], off
	global_load_dwordx4 v[158:161], v[224:225], off offset:64
	global_load_dwordx4 v[120:123], v[232:233], off offset:64
	global_load_dwordx4 v[162:165], v[224:225], off offset:128
	global_load_dwordx4 v[124:127], v[232:233], off offset:128
	global_load_dwordx4 v[166:169], v[224:225], off offset:192
	global_load_dwordx4 v[134:137], v[232:233], off offset:192
	global_load_dwordx4 v[208:211], v[226:227], off
	global_load_dwordx4 v[138:141], v[234:235], off
	global_load_dwordx4 v[212:215], v[226:227], off offset:64
	global_load_dwordx4 v[200:203], v[234:235], off offset:64
	global_load_dwordx4 v[216:219], v[226:227], off offset:128
	global_load_dwordx4 v[204:207], v[234:235], off offset:128
	global_load_dwordx4 v[220:223], v[226:227], off offset:192
	global_load_dwordx4 v[244:247], v[234:235], off offset:192
	s_waitcnt vmcnt(0)
	v_pk_mul_f32 v[60:61], v[60:61], v[116:117]
	v_pk_add_f32 v[154:155], v[154:155], v[132:133] op_sel_hi:[1,0] neg_lo:[0,1] neg_hi:[0,1]
	v_pk_mul_f32 v[62:63], v[62:63], v[118:119]
	v_pk_add_f32 v[156:157], v[156:157], v[132:133] op_sel_hi:[1,0] neg_lo:[0,1] neg_hi:[0,1]
	v_pk_mul_f32 v[154:155], v[154:155], v[132:133] op_sel:[0,1] op_sel_hi:[1,1]
	v_pk_mul_f32 v[156:157], v[156:157], v[132:133] op_sel:[0,1] op_sel_hi:[1,1]
	v_pk_fma_f32 v[154:155], v[96:97], v[154:155], v[112:113]
	v_pk_fma_f32 v[156:157], v[98:99], v[156:157], v[114:115]
	v_pk_fma_f32 v[60:61], v[154:155], s[8:9], v[60:61] op_sel_hi:[1,0,1]
	v_pk_fma_f32 v[62:63], v[156:157], s[8:9], v[62:63] op_sel_hi:[1,0,1]
	global_store_dwordx4 v[228:229], v[60:63], off
	v_pk_mul_f32 v[56:57], v[56:57], v[120:121]
	v_pk_add_f32 v[158:159], v[158:159], v[132:133] op_sel_hi:[1,0] neg_lo:[0,1] neg_hi:[0,1]
	v_pk_mul_f32 v[58:59], v[58:59], v[122:123]
	v_pk_add_f32 v[160:161], v[160:161], v[132:133] op_sel_hi:[1,0] neg_lo:[0,1] neg_hi:[0,1]
	v_pk_mul_f32 v[158:159], v[158:159], v[132:133] op_sel:[0,1] op_sel_hi:[1,1]
	v_pk_mul_f32 v[160:161], v[160:161], v[132:133] op_sel:[0,1] op_sel_hi:[1,1]
	v_pk_fma_f32 v[158:159], v[100:101], v[158:159], v[150:151]
	v_pk_fma_f32 v[160:161], v[102:103], v[160:161], v[152:153]
	v_pk_fma_f32 v[56:57], v[158:159], s[8:9], v[56:57] op_sel_hi:[1,0,1]
	v_pk_fma_f32 v[58:59], v[160:161], s[8:9], v[58:59] op_sel_hi:[1,0,1]
	global_store_dwordx4 v[228:229], v[56:59], off offset:64
	v_pk_mul_f32 v[52:53], v[52:53], v[124:125]
	v_pk_add_f32 v[162:163], v[162:163], v[132:133] op_sel_hi:[1,0] neg_lo:[0,1] neg_hi:[0,1]
	v_pk_mul_f32 v[54:55], v[54:55], v[126:127]
	v_pk_add_f32 v[164:165], v[164:165], v[132:133] op_sel_hi:[1,0] neg_lo:[0,1] neg_hi:[0,1]
	v_pk_mul_f32 v[162:163], v[162:163], v[132:133] op_sel:[0,1] op_sel_hi:[1,1]
	v_pk_mul_f32 v[164:165], v[164:165], v[132:133] op_sel:[0,1] op_sel_hi:[1,1]
	v_pk_fma_f32 v[162:163], v[104:105], v[162:163], v[142:143]
	v_pk_fma_f32 v[164:165], v[106:107], v[164:165], v[144:145]
	v_pk_fma_f32 v[52:53], v[162:163], s[8:9], v[52:53] op_sel_hi:[1,0,1]
	v_pk_fma_f32 v[54:55], v[164:165], s[8:9], v[54:55] op_sel_hi:[1,0,1]
	global_store_dwordx4 v[228:229], v[52:55], off offset:128
	v_pk_mul_f32 v[48:49], v[48:49], v[134:135]
	v_pk_add_f32 v[166:167], v[166:167], v[132:133] op_sel_hi:[1,0] neg_lo:[0,1] neg_hi:[0,1]
	v_pk_mul_f32 v[50:51], v[50:51], v[136:137]
	v_pk_add_f32 v[168:169], v[168:169], v[132:133] op_sel_hi:[1,0] neg_lo:[0,1] neg_hi:[0,1]
	v_pk_mul_f32 v[166:167], v[166:167], v[132:133] op_sel:[0,1] op_sel_hi:[1,1]
	v_pk_mul_f32 v[168:169], v[168:169], v[132:133] op_sel:[0,1] op_sel_hi:[1,1]
	v_pk_fma_f32 v[166:167], v[108:109], v[166:167], v[146:147]
	v_pk_fma_f32 v[168:169], v[110:111], v[168:169], v[148:149]
	v_pk_fma_f32 v[48:49], v[166:167], s[8:9], v[48:49] op_sel_hi:[1,0,1]
	v_pk_fma_f32 v[50:51], v[168:169], s[8:9], v[50:51] op_sel_hi:[1,0,1]
	global_store_dwordx4 v[228:229], v[48:51], off offset:192
	v_pk_mul_f32 v[44:45], v[44:45], v[138:139]
	v_pk_add_f32 v[208:209], v[208:209], v[128:129] op_sel_hi:[1,0] neg_lo:[0,1] neg_hi:[0,1]
	v_pk_mul_f32 v[46:47], v[46:47], v[140:141]
	v_pk_add_f32 v[210:211], v[210:211], v[128:129] op_sel_hi:[1,0] neg_lo:[0,1] neg_hi:[0,1]
	v_pk_mul_f32 v[208:209], v[208:209], v[170:171] op_sel_hi:[1,0]
	v_pk_mul_f32 v[210:211], v[210:211], v[170:171] op_sel_hi:[1,0]
	v_pk_fma_f32 v[208:209], v[96:97], v[208:209], v[112:113]
	v_pk_fma_f32 v[210:211], v[98:99], v[210:211], v[114:115]
	v_pk_fma_f32 v[44:45], v[208:209], s[8:9], v[44:45] op_sel_hi:[1,0,1]
	v_pk_fma_f32 v[46:47], v[210:211], s[8:9], v[46:47] op_sel_hi:[1,0,1]
	global_store_dwordx4 v[230:231], v[44:47], off
	v_pk_mul_f32 v[40:41], v[40:41], v[200:201]
	v_pk_add_f32 v[212:213], v[212:213], v[128:129] op_sel_hi:[1,0] neg_lo:[0,1] neg_hi:[0,1]
	v_pk_mul_f32 v[42:43], v[42:43], v[202:203]
	v_pk_add_f32 v[214:215], v[214:215], v[128:129] op_sel_hi:[1,0] neg_lo:[0,1] neg_hi:[0,1]
	v_pk_mul_f32 v[212:213], v[212:213], v[170:171] op_sel_hi:[1,0]
	v_pk_mul_f32 v[214:215], v[214:215], v[170:171] op_sel_hi:[1,0]
	v_pk_fma_f32 v[212:213], v[100:101], v[212:213], v[150:151]
	v_pk_fma_f32 v[214:215], v[102:103], v[214:215], v[152:153]
	v_pk_fma_f32 v[40:41], v[212:213], s[8:9], v[40:41] op_sel_hi:[1,0,1]
	v_pk_fma_f32 v[42:43], v[214:215], s[8:9], v[42:43] op_sel_hi:[1,0,1]
	global_store_dwordx4 v[230:231], v[40:43], off offset:64
	v_pk_mul_f32 v[36:37], v[36:37], v[204:205]
	v_pk_add_f32 v[216:217], v[216:217], v[128:129] op_sel_hi:[1,0] neg_lo:[0,1] neg_hi:[0,1]
	v_pk_mul_f32 v[38:39], v[38:39], v[206:207]
	v_pk_add_f32 v[218:219], v[218:219], v[128:129] op_sel_hi:[1,0] neg_lo:[0,1] neg_hi:[0,1]
	v_pk_mul_f32 v[216:217], v[216:217], v[170:171] op_sel_hi:[1,0]
	v_pk_mul_f32 v[218:219], v[218:219], v[170:171] op_sel_hi:[1,0]
	v_pk_fma_f32 v[216:217], v[104:105], v[216:217], v[142:143]
	v_pk_fma_f32 v[218:219], v[106:107], v[218:219], v[144:145]
	v_pk_fma_f32 v[36:37], v[216:217], s[8:9], v[36:37] op_sel_hi:[1,0,1]
	v_pk_fma_f32 v[38:39], v[218:219], s[8:9], v[38:39] op_sel_hi:[1,0,1]
	global_store_dwordx4 v[230:231], v[36:39], off offset:128
	v_pk_mul_f32 v[32:33], v[32:33], v[244:245]
	v_pk_add_f32 v[220:221], v[220:221], v[128:129] op_sel_hi:[1,0] neg_lo:[0,1] neg_hi:[0,1]
	v_pk_mul_f32 v[34:35], v[34:35], v[246:247]
	v_pk_add_f32 v[222:223], v[222:223], v[128:129] op_sel_hi:[1,0] neg_lo:[0,1] neg_hi:[0,1]
	v_pk_mul_f32 v[220:221], v[220:221], v[170:171] op_sel_hi:[1,0]
	v_pk_mul_f32 v[222:223], v[222:223], v[170:171] op_sel_hi:[1,0]
	v_pk_fma_f32 v[220:221], v[108:109], v[220:221], v[146:147]
	v_pk_fma_f32 v[222:223], v[110:111], v[222:223], v[148:149]
	v_pk_fma_f32 v[32:33], v[220:221], s[8:9], v[32:33] op_sel_hi:[1,0,1]
	v_pk_fma_f32 v[34:35], v[222:223], s[8:9], v[34:35] op_sel_hi:[1,0,1]
	global_store_dwordx4 v[230:231], v[32:35], off offset:192
	v_add_u32_e32 v254, 64, v237
	v_add_u32_e32 v236, 0xfffff000, v254
	v_cmp_lt_i32_e32 vcc, 0xfff, v254
	v_lshrrev_b32_e32 v236, 10, v236
	v_lshlrev_b32_e32 v224, 3, v254
	v_lshlrev_b32_e32 v254, 12, v254
	v_add_u32_e32 v236, 1, v236
	v_mov_b32_e32 v225, 0
	v_cndmask_b32_e32 v236, 0, v236, vcc
	v_lshl_add_u64 v[224:225], v[224:225], 0, s[10:11]
	v_lshl_add_u64 v[228:229], v[254:255], 0, v[250:251]
	v_add_u32_e32 v236, s4, v236
	v_mad_i64_i32 v[232:233], s[0:1], v236, s33, v[252:253]
	global_load_dwordx2 v[132:133], v[224:225], off
	v_lshl_add_u64 v[224:225], v[254:255], 0, v[248:249]
	v_add_u32_e32 v254, 80, v237
	v_add_u32_e32 v236, 0xfffff000, v254
	v_cmp_lt_i32_e32 vcc, 0xfff, v254
	v_lshrrev_b32_e32 v236, 10, v236
	v_lshlrev_b32_e32 v226, 3, v254
	v_lshlrev_b32_e32 v254, 12, v254
	v_add_u32_e32 v236, 1, v236
	v_mov_b32_e32 v227, 0
	v_cndmask_b32_e32 v236, 0, v236, vcc
	v_lshl_add_u64 v[226:227], v[226:227], 0, s[10:11]
	v_lshl_add_u64 v[230:231], v[254:255], 0, v[250:251]
	v_add_u32_e32 v236, s4, v236
	v_mad_i64_i32 v[234:235], s[0:1], v236, s33, v[252:253]
	global_load_dword v128, v[226:227], off
	global_load_dword v170, v[226:227], off offset:4
	v_lshl_add_u64 v[226:227], v[254:255], 0, v[248:249]
	global_load_dwordx4 v[154:157], v[224:225], off
	global_load_dwordx4 v[116:119], v[232:233], off
	global_load_dwordx4 v[158:161], v[224:225], off offset:64
	global_load_dwordx4 v[120:123], v[232:233], off offset:64
	global_load_dwordx4 v[162:165], v[224:225], off offset:128
	global_load_dwordx4 v[124:127], v[232:233], off offset:128
	global_load_dwordx4 v[166:169], v[224:225], off offset:192
	global_load_dwordx4 v[134:137], v[232:233], off offset:192
	global_load_dwordx4 v[208:211], v[226:227], off
	global_load_dwordx4 v[138:141], v[234:235], off
	global_load_dwordx4 v[212:215], v[226:227], off offset:64
	global_load_dwordx4 v[200:203], v[234:235], off offset:64
	global_load_dwordx4 v[216:219], v[226:227], off offset:128
	global_load_dwordx4 v[204:207], v[234:235], off offset:128
	global_load_dwordx4 v[220:223], v[226:227], off offset:192
	global_load_dwordx4 v[244:247], v[234:235], off offset:192
	s_waitcnt vmcnt(0)
	v_pk_mul_f32 v[28:29], v[28:29], v[116:117]
	v_pk_add_f32 v[154:155], v[154:155], v[132:133] op_sel_hi:[1,0] neg_lo:[0,1] neg_hi:[0,1]
	v_pk_mul_f32 v[30:31], v[30:31], v[118:119]
	v_pk_add_f32 v[156:157], v[156:157], v[132:133] op_sel_hi:[1,0] neg_lo:[0,1] neg_hi:[0,1]
	v_pk_mul_f32 v[154:155], v[154:155], v[132:133] op_sel:[0,1] op_sel_hi:[1,1]
	v_pk_mul_f32 v[156:157], v[156:157], v[132:133] op_sel:[0,1] op_sel_hi:[1,1]
	v_pk_fma_f32 v[154:155], v[96:97], v[154:155], v[112:113]
	v_pk_fma_f32 v[156:157], v[98:99], v[156:157], v[114:115]
	v_pk_fma_f32 v[28:29], v[154:155], s[8:9], v[28:29] op_sel_hi:[1,0,1]
	v_pk_fma_f32 v[30:31], v[156:157], s[8:9], v[30:31] op_sel_hi:[1,0,1]
	global_store_dwordx4 v[228:229], v[28:31], off
	v_pk_mul_f32 v[24:25], v[24:25], v[120:121]
	v_pk_add_f32 v[158:159], v[158:159], v[132:133] op_sel_hi:[1,0] neg_lo:[0,1] neg_hi:[0,1]
	v_pk_mul_f32 v[26:27], v[26:27], v[122:123]
	v_pk_add_f32 v[160:161], v[160:161], v[132:133] op_sel_hi:[1,0] neg_lo:[0,1] neg_hi:[0,1]
	v_pk_mul_f32 v[158:159], v[158:159], v[132:133] op_sel:[0,1] op_sel_hi:[1,1]
	v_pk_mul_f32 v[160:161], v[160:161], v[132:133] op_sel:[0,1] op_sel_hi:[1,1]
	v_pk_fma_f32 v[158:159], v[100:101], v[158:159], v[150:151]
	v_pk_fma_f32 v[160:161], v[102:103], v[160:161], v[152:153]
	v_pk_fma_f32 v[24:25], v[158:159], s[8:9], v[24:25] op_sel_hi:[1,0,1]
	v_pk_fma_f32 v[26:27], v[160:161], s[8:9], v[26:27] op_sel_hi:[1,0,1]
	global_store_dwordx4 v[228:229], v[24:27], off offset:64
	v_pk_mul_f32 v[20:21], v[20:21], v[124:125]
	v_pk_add_f32 v[162:163], v[162:163], v[132:133] op_sel_hi:[1,0] neg_lo:[0,1] neg_hi:[0,1]
	v_pk_mul_f32 v[22:23], v[22:23], v[126:127]
	v_pk_add_f32 v[164:165], v[164:165], v[132:133] op_sel_hi:[1,0] neg_lo:[0,1] neg_hi:[0,1]
	v_pk_mul_f32 v[162:163], v[162:163], v[132:133] op_sel:[0,1] op_sel_hi:[1,1]
	v_pk_mul_f32 v[164:165], v[164:165], v[132:133] op_sel:[0,1] op_sel_hi:[1,1]
	v_pk_fma_f32 v[162:163], v[104:105], v[162:163], v[142:143]
	v_pk_fma_f32 v[164:165], v[106:107], v[164:165], v[144:145]
	v_pk_fma_f32 v[20:21], v[162:163], s[8:9], v[20:21] op_sel_hi:[1,0,1]
	v_pk_fma_f32 v[22:23], v[164:165], s[8:9], v[22:23] op_sel_hi:[1,0,1]
	global_store_dwordx4 v[228:229], v[20:23], off offset:128
	v_pk_mul_f32 v[16:17], v[16:17], v[134:135]
	v_pk_add_f32 v[166:167], v[166:167], v[132:133] op_sel_hi:[1,0] neg_lo:[0,1] neg_hi:[0,1]
	v_pk_mul_f32 v[18:19], v[18:19], v[136:137]
	v_pk_add_f32 v[168:169], v[168:169], v[132:133] op_sel_hi:[1,0] neg_lo:[0,1] neg_hi:[0,1]
	v_pk_mul_f32 v[166:167], v[166:167], v[132:133] op_sel:[0,1] op_sel_hi:[1,1]
	v_pk_mul_f32 v[168:169], v[168:169], v[132:133] op_sel:[0,1] op_sel_hi:[1,1]
	v_pk_fma_f32 v[166:167], v[108:109], v[166:167], v[146:147]
	v_pk_fma_f32 v[168:169], v[110:111], v[168:169], v[148:149]
	v_pk_fma_f32 v[16:17], v[166:167], s[8:9], v[16:17] op_sel_hi:[1,0,1]
	v_pk_fma_f32 v[18:19], v[168:169], s[8:9], v[18:19] op_sel_hi:[1,0,1]
	global_store_dwordx4 v[228:229], v[16:19], off offset:192
	v_pk_mul_f32 v[8:9], v[8:9], v[138:139]
	v_pk_add_f32 v[208:209], v[208:209], v[128:129] op_sel_hi:[1,0] neg_lo:[0,1] neg_hi:[0,1]
	v_pk_mul_f32 v[10:11], v[10:11], v[140:141]
	v_pk_add_f32 v[210:211], v[210:211], v[128:129] op_sel_hi:[1,0] neg_lo:[0,1] neg_hi:[0,1]
	v_pk_mul_f32 v[208:209], v[208:209], v[170:171] op_sel_hi:[1,0]
	v_pk_mul_f32 v[210:211], v[210:211], v[170:171] op_sel_hi:[1,0]
	v_pk_fma_f32 v[208:209], v[96:97], v[208:209], v[112:113]
	v_pk_fma_f32 v[210:211], v[98:99], v[210:211], v[114:115]
	v_pk_fma_f32 v[8:9], v[208:209], s[8:9], v[8:9] op_sel_hi:[1,0,1]
	v_pk_fma_f32 v[10:11], v[210:211], s[8:9], v[10:11] op_sel_hi:[1,0,1]
	global_store_dwordx4 v[230:231], v[8:11], off
	v_pk_mul_f32 v[4:5], v[4:5], v[200:201]
	v_pk_add_f32 v[212:213], v[212:213], v[128:129] op_sel_hi:[1,0] neg_lo:[0,1] neg_hi:[0,1]
	v_pk_mul_f32 v[6:7], v[6:7], v[202:203]
	v_pk_add_f32 v[214:215], v[214:215], v[128:129] op_sel_hi:[1,0] neg_lo:[0,1] neg_hi:[0,1]
	v_pk_mul_f32 v[212:213], v[212:213], v[170:171] op_sel_hi:[1,0]
	v_pk_mul_f32 v[214:215], v[214:215], v[170:171] op_sel_hi:[1,0]
	v_pk_fma_f32 v[212:213], v[100:101], v[212:213], v[150:151]
	v_pk_fma_f32 v[214:215], v[102:103], v[214:215], v[152:153]
	v_pk_fma_f32 v[4:5], v[212:213], s[8:9], v[4:5] op_sel_hi:[1,0,1]
	v_pk_fma_f32 v[6:7], v[214:215], s[8:9], v[6:7] op_sel_hi:[1,0,1]
	global_store_dwordx4 v[230:231], v[4:7], off offset:64
	v_pk_mul_f32 v[12:13], v[12:13], v[204:205]
	v_pk_add_f32 v[216:217], v[216:217], v[128:129] op_sel_hi:[1,0] neg_lo:[0,1] neg_hi:[0,1]
	v_pk_mul_f32 v[14:15], v[14:15], v[206:207]
	v_pk_add_f32 v[218:219], v[218:219], v[128:129] op_sel_hi:[1,0] neg_lo:[0,1] neg_hi:[0,1]
	v_pk_mul_f32 v[216:217], v[216:217], v[170:171] op_sel_hi:[1,0]
	v_pk_mul_f32 v[218:219], v[218:219], v[170:171] op_sel_hi:[1,0]
	v_pk_fma_f32 v[216:217], v[104:105], v[216:217], v[142:143]
	v_pk_fma_f32 v[218:219], v[106:107], v[218:219], v[144:145]
	v_pk_fma_f32 v[12:13], v[216:217], s[8:9], v[12:13] op_sel_hi:[1,0,1]
	v_pk_fma_f32 v[14:15], v[218:219], s[8:9], v[14:15] op_sel_hi:[1,0,1]
	global_store_dwordx4 v[230:231], v[12:15], off offset:128
	v_pk_mul_f32 v[0:1], v[0:1], v[244:245]
	v_pk_add_f32 v[220:221], v[220:221], v[128:129] op_sel_hi:[1,0] neg_lo:[0,1] neg_hi:[0,1]
	v_pk_mul_f32 v[2:3], v[2:3], v[246:247]
	v_pk_add_f32 v[222:223], v[222:223], v[128:129] op_sel_hi:[1,0] neg_lo:[0,1] neg_hi:[0,1]
	v_pk_mul_f32 v[220:221], v[220:221], v[170:171] op_sel_hi:[1,0]
	v_pk_mul_f32 v[222:223], v[222:223], v[170:171] op_sel_hi:[1,0]
	v_pk_fma_f32 v[220:221], v[108:109], v[220:221], v[146:147]
	v_pk_fma_f32 v[222:223], v[110:111], v[222:223], v[148:149]
	v_pk_fma_f32 v[0:1], v[220:221], s[8:9], v[0:1] op_sel_hi:[1,0,1]
	v_pk_fma_f32 v[2:3], v[222:223], s[8:9], v[2:3] op_sel_hi:[1,0,1]
	global_store_dwordx4 v[230:231], v[0:3], off offset:192
	v_readlane_b32 s9, v242, 26
	v_readlane_b32 s10, v242, 27
	v_readlane_b32 s11, v242, 28
	v_readlane_b32 s12, v242, 29
	v_readlane_b32 s13, v242, 30
	v_readlane_b32 s14, v242, 31
	v_readlane_b32 s15, v242, 32
	v_readlane_b32 s16, v242, 33
	v_readlane_b32 s17, v242, 34
	v_readlane_b32 s18, v242, 35
	v_readlane_b32 s19, v242, 36
	v_readlane_b32 s20, v242, 37
	v_readlane_b32 s21, v242, 38
	v_readlane_b32 s22, v242, 39
	v_readlane_b32 s23, v242, 40
	s_mov_b64 s[24:25], 0x5000
	s_movk_i32 s6, 0xfff
	s_waitcnt lgkmcnt(0)
	s_barrier
	s_cmpk_gt_i32 s5, 0xff
	s_cbranch_scc0 .LBB0_52

.Lk_out:
	s_waitcnt lgkmcnt(0)
	v_mfma_f32_16x16x32_bf16 v[92:95], v[166:169], v[134:137], v[92:95]
	s_waitcnt vmcnt(10)
	s_barrier
	v_mfma_f32_16x16x32_bf16 v[88:91], v[200:203], v[134:137], v[88:91]
	s_cmp_eq_u32 s35, 0xf000
	s_cselect_b32 s38, s37, s36
	s_add_u32 s39, s34, s35
	v_mfma_f32_16x16x32_bf16 v[84:87], v[204:207], v[134:137], v[84:87]
	v_add_u32_e32 v170, s38, v170
	v_add_u32_e32 v172, s38, v172
	s_add_u32 s35, s35, s38
	v_mfma_f32_16x16x32_bf16 v[80:83], v[208:211], v[134:137], v[80:83]
	ds_read_b128 v[212:215], v170
	ds_read_b128 v[216:219], v170 offset:1024
	ds_read_b128 v[220:223], v170 offset:2048
	ds_read_b128 v[224:227], v170 offset:3072
	ds_read_b128 v[228:231], v170 offset:4096
	ds_read_b128 v[232:235], v170 offset:5120
	v_mfma_f32_16x16x32_bf16 v[76:79], v[166:169], v[138:141], v[76:79]
	v_mfma_f32_16x16x32_bf16 v[72:75], v[200:203], v[138:141], v[72:75]
	v_mfma_f32_16x16x32_bf16 v[68:71], v[204:207], v[138:141], v[68:71]
	ds_read_b128 v[244:247], v172 offset:12288
	ds_read_b128 v[248:251], v172 offset:13312
	ds_read_b128 v[252:255], v172 offset:14336
	ds_read_b128 v[116:119], v172 offset:15360
	v_mfma_f32_16x16x32_bf16 v[64:67], v[208:211], v[138:141], v[64:67]
	v_mfma_f32_16x16x32_bf16 v[60:63], v[166:169], v[150:153], v[60:63]
	s_mov_b32 m0, s39
	v_mfma_f32_16x16x32_bf16 v[56:59], v[200:203], v[150:153], v[56:59]
	global_load_lds_dwordx4 v[124:125], off
	v_lshl_add_u64 v[124:125], v[124:125], 0, 64
	v_mfma_f32_16x16x32_bf16 v[52:55], v[204:207], v[150:153], v[52:55]
	s_add_u32 m0, s39, 0x1000
	v_mfma_f32_16x16x32_bf16 v[48:51], v[208:211], v[150:153], v[48:51]
	global_load_lds_dwordx4 v[122:123], off
	v_lshl_add_u64 v[122:123], v[122:123], 0, 64
	v_mfma_f32_16x16x32_bf16 v[44:47], v[166:169], v[154:157], v[44:47]
	s_add_u32 m0, s39, 0x2000
	v_mfma_f32_16x16x32_bf16 v[40:43], v[200:203], v[154:157], v[40:43]
	global_load_lds_dwordx4 v[120:121], off
	v_lshl_add_u64 v[120:121], v[120:121], 0, 64
	v_mfma_f32_16x16x32_bf16 v[36:39], v[204:207], v[154:157], v[36:39]
	s_add_u32 m0, s39, 0x3000
	v_mfma_f32_16x16x32_bf16 v[32:35], v[208:211], v[154:157], v[32:35]
	global_load_lds_dwordx4 v[236:237], off
	v_lshl_add_u64 v[236:237], v[236:237], 0, 64
	v_mfma_f32_16x16x32_bf16 v[28:31], v[166:169], v[158:161], v[28:31]
	s_add_u32 m0, s39, 0x4000
	v_mfma_f32_16x16x32_bf16 v[24:27], v[200:203], v[158:161], v[24:27]
	global_load_lds_dwordx4 v[126:127], off
	v_lshl_add_u64 v[126:127], v[126:127], 0, 64
	v_mfma_f32_16x16x32_bf16 v[20:23], v[204:207], v[158:161], v[20:23]
	v_mfma_f32_16x16x32_bf16 v[16:19], v[208:211], v[158:161], v[16:19]
	v_mfma_f32_16x16x32_bf16 v[8:11], v[166:169], v[162:165], v[8:11]
	v_mfma_f32_16x16x32_bf16 v[4:7], v[200:203], v[162:165], v[4:7]
	v_mfma_f32_16x16x32_bf16 v[12:15], v[204:207], v[162:165], v[12:15]
	v_mfma_f32_16x16x32_bf16 v[0:3], v[208:211], v[162:165], v[0:3]
	s_waitcnt lgkmcnt(0)
	v_mfma_f32_16x16x32_bf16 v[92:95], v[244:247], v[212:215], v[92:95]
	s_waitcnt vmcnt(10)
	s_barrier
	v_mfma_f32_16x16x32_bf16 v[88:91], v[248:251], v[212:215], v[88:91]
	s_cmp_eq_u32 s35, 0xf000
	s_cselect_b32 s38, s37, s36
	s_add_u32 s39, s34, s35
	v_mfma_f32_16x16x32_bf16 v[84:87], v[252:255], v[212:215], v[84:87]
	v_add_u32_e32 v170, s38, v170
	v_add_u32_e32 v172, s38, v172
	s_add_u32 s35, s35, s38
	v_mfma_f32_16x16x32_bf16 v[80:83], v[116:119], v[212:215], v[80:83]
	ds_read_b128 v[134:137], v170
	ds_read_b128 v[138:141], v170 offset:1024
	ds_read_b128 v[150:153], v170 offset:2048
	ds_read_b128 v[154:157], v170 offset:3072
	ds_read_b128 v[158:161], v170 offset:4096
	ds_read_b128 v[162:165], v170 offset:5120
	v_mfma_f32_16x16x32_bf16 v[76:79], v[244:247], v[216:219], v[76:79]
	v_mfma_f32_16x16x32_bf16 v[72:75], v[248:251], v[216:219], v[72:75]
	v_mfma_f32_16x16x32_bf16 v[68:71], v[252:255], v[216:219], v[68:71]
	ds_read_b128 v[166:169], v172 offset:12288
	ds_read_b128 v[200:203], v172 offset:13312
	ds_read_b128 v[204:207], v172 offset:14336
	ds_read_b128 v[208:211], v172 offset:15360
	v_mfma_f32_16x16x32_bf16 v[64:67], v[116:119], v[216:219], v[64:67]
	v_mfma_f32_16x16x32_bf16 v[60:63], v[244:247], v[220:223], v[60:63]
	s_mov_b32 m0, s39
	v_mfma_f32_16x16x32_bf16 v[56:59], v[248:251], v[220:223], v[56:59]
	global_load_lds_dwordx4 v[124:125], off
	v_lshl_add_u64 v[124:125], v[124:125], 0, 64
	v_mfma_f32_16x16x32_bf16 v[52:55], v[252:255], v[220:223], v[52:55]
	s_add_u32 m0, s39, 0x1000
	v_mfma_f32_16x16x32_bf16 v[48:51], v[116:119], v[220:223], v[48:51]
	global_load_lds_dwordx4 v[122:123], off
	v_lshl_add_u64 v[122:123], v[122:123], 0, 64
	v_mfma_f32_16x16x32_bf16 v[44:47], v[244:247], v[224:227], v[44:47]
	s_add_u32 m0, s39, 0x2000
	v_mfma_f32_16x16x32_bf16 v[40:43], v[248:251], v[224:227], v[40:43]
	global_load_lds_dwordx4 v[120:121], off
	v_lshl_add_u64 v[120:121], v[120:121], 0, 64
	v_mfma_f32_16x16x32_bf16 v[36:39], v[252:255], v[224:227], v[36:39]
	s_add_u32 m0, s39, 0x3000
	v_mfma_f32_16x16x32_bf16 v[32:35], v[116:119], v[224:227], v[32:35]
	global_load_lds_dwordx4 v[236:237], off
	v_lshl_add_u64 v[236:237], v[236:237], 0, 64
	v_mfma_f32_16x16x32_bf16 v[28:31], v[244:247], v[228:231], v[28:31]
	s_add_u32 m0, s39, 0x4000
	v_mfma_f32_16x16x32_bf16 v[24:27], v[248:251], v[228:231], v[24:27]
	global_load_lds_dwordx4 v[126:127], off
	v_lshl_add_u64 v[126:127], v[126:127], 0, 64
	v_mfma_f32_16x16x32_bf16 v[20:23], v[252:255], v[228:231], v[20:23]
	s_add_i32 s41, s41, -1
	s_cmp_eq_u32 s41, 0
	v_mfma_f32_16x16x32_bf16 v[16:19], v[116:119], v[228:231], v[16:19]
	v_mfma_f32_16x16x32_bf16 v[8:11], v[244:247], v[232:235], v[8:11]
	v_mfma_f32_16x16x32_bf16 v[4:7], v[248:251], v[232:235], v[4:7]
	v_mfma_f32_16x16x32_bf16 v[12:15], v[252:255], v[232:235], v[12:15]
	v_mfma_f32_16x16x32_bf16 v[0:3], v[116:119], v[232:235], v[0:3]
	s_cbranch_scc0 .Lk_out
	s_waitcnt lgkmcnt(0)
	v_mfma_f32_16x16x32_bf16 v[92:95], v[166:169], v[134:137], v[92:95]
	s_waitcnt vmcnt(10)
	s_barrier
	v_mfma_f32_16x16x32_bf16 v[88:91], v[200:203], v[134:137], v[88:91]
	s_cmp_eq_u32 s35, 0xf000
	s_cselect_b32 s38, s37, s36
	v_mfma_f32_16x16x32_bf16 v[84:87], v[204:207], v[134:137], v[84:87]
	v_add_u32_e32 v170, s38, v170
	v_add_u32_e32 v172, s38, v172
	s_add_u32 s35, s35, s38
	v_mfma_f32_16x16x32_bf16 v[80:83], v[208:211], v[134:137], v[80:83]
	ds_read_b128 v[212:215], v170
	ds_read_b128 v[216:219], v170 offset:1024
	ds_read_b128 v[220:223], v170 offset:2048
	ds_read_b128 v[224:227], v170 offset:3072
	ds_read_b128 v[228:231], v170 offset:4096
	ds_read_b128 v[232:235], v170 offset:5120
	v_mfma_f32_16x16x32_bf16 v[76:79], v[166:169], v[138:141], v[76:79]
	v_mfma_f32_16x16x32_bf16 v[72:75], v[200:203], v[138:141], v[72:75]
	v_mfma_f32_16x16x32_bf16 v[68:71], v[204:207], v[138:141], v[68:71]
	ds_read_b128 v[244:247], v172 offset:12288
	ds_read_b128 v[248:251], v172 offset:13312
	ds_read_b128 v[252:255], v172 offset:14336
	ds_read_b128 v[116:119], v172 offset:15360
	v_mfma_f32_16x16x32_bf16 v[64:67], v[208:211], v[138:141], v[64:67]
	v_mfma_f32_16x16x32_bf16 v[60:63], v[166:169], v[150:153], v[60:63]
	v_mfma_f32_16x16x32_bf16 v[56:59], v[200:203], v[150:153], v[56:59]
	v_mfma_f32_16x16x32_bf16 v[52:55], v[204:207], v[150:153], v[52:55]
	v_mfma_f32_16x16x32_bf16 v[48:51], v[208:211], v[150:153], v[48:51]
	v_mfma_f32_16x16x32_bf16 v[44:47], v[166:169], v[154:157], v[44:47]
	v_mfma_f32_16x16x32_bf16 v[40:43], v[200:203], v[154:157], v[40:43]
	v_mfma_f32_16x16x32_bf16 v[36:39], v[204:207], v[154:157], v[36:39]
	v_mfma_f32_16x16x32_bf16 v[32:35], v[208:211], v[154:157], v[32:35]
	v_mfma_f32_16x16x32_bf16 v[28:31], v[166:169], v[158:161], v[28:31]
	v_mfma_f32_16x16x32_bf16 v[24:27], v[200:203], v[158:161], v[24:27]
	v_mfma_f32_16x16x32_bf16 v[20:23], v[204:207], v[158:161], v[20:23]
	v_mfma_f32_16x16x32_bf16 v[16:19], v[208:211], v[158:161], v[16:19]
	v_mfma_f32_16x16x32_bf16 v[8:11], v[166:169], v[162:165], v[8:11]
	v_mfma_f32_16x16x32_bf16 v[4:7], v[200:203], v[162:165], v[4:7]
	v_mfma_f32_16x16x32_bf16 v[12:15], v[204:207], v[162:165], v[12:15]
	v_mfma_f32_16x16x32_bf16 v[0:3], v[208:211], v[162:165], v[0:3]
	s_waitcnt lgkmcnt(0)
	v_mfma_f32_16x16x32_bf16 v[92:95], v[244:247], v[212:215], v[92:95]
	s_waitcnt vmcnt(5)
	s_barrier
	v_mfma_f32_16x16x32_bf16 v[88:91], v[248:251], v[212:215], v[88:91]
	s_cmp_eq_u32 s35, 0xf000
	s_cselect_b32 s38, s37, s36
	v_mfma_f32_16x16x32_bf16 v[84:87], v[252:255], v[212:215], v[84:87]
	v_add_u32_e32 v170, s38, v170
	v_add_u32_e32 v172, s38, v172
	s_add_u32 s35, s35, s38
	v_mfma_f32_16x16x32_bf16 v[80:83], v[116:119], v[212:215], v[80:83]
	ds_read_b128 v[134:137], v170
	ds_read_b128 v[138:141], v170 offset:1024
	ds_read_b128 v[150:153], v170 offset:2048
	ds_read_b128 v[154:157], v170 offset:3072
	ds_read_b128 v[158:161], v170 offset:4096
	ds_read_b128 v[162:165], v170 offset:5120
	v_mfma_f32_16x16x32_bf16 v[76:79], v[244:247], v[216:219], v[76:79]
	v_mfma_f32_16x16x32_bf16 v[72:75], v[248:251], v[216:219], v[72:75]
	v_mfma_f32_16x16x32_bf16 v[68:71], v[252:255], v[216:219], v[68:71]
	ds_read_b128 v[166:169], v172 offset:12288
	ds_read_b128 v[200:203], v172 offset:13312
	ds_read_b128 v[204:207], v172 offset:14336
	ds_read_b128 v[208:211], v172 offset:15360
	v_mfma_f32_16x16x32_bf16 v[64:67], v[116:119], v[216:219], v[64:67]
	v_mfma_f32_16x16x32_bf16 v[60:63], v[244:247], v[220:223], v[60:63]
	v_mfma_f32_16x16x32_bf16 v[56:59], v[248:251], v[220:223], v[56:59]
	v_mfma_f32_16x16x32_bf16 v[52:55], v[252:255], v[220:223], v[52:55]
	v_mfma_f32_16x16x32_bf16 v[48:51], v[116:119], v[220:223], v[48:51]
	v_mfma_f32_16x16x32_bf16 v[44:47], v[244:247], v[224:227], v[44:47]
	v_mfma_f32_16x16x32_bf16 v[40:43], v[248:251], v[224:227], v[40:43]
	v_mfma_f32_16x16x32_bf16 v[36:39], v[252:255], v[224:227], v[36:39]
	v_mfma_f32_16x16x32_bf16 v[32:35], v[116:119], v[224:227], v[32:35]
	v_mfma_f32_16x16x32_bf16 v[28:31], v[244:247], v[228:231], v[28:31]
	v_mfma_f32_16x16x32_bf16 v[24:27], v[248:251], v[228:231], v[24:27]
	v_mfma_f32_16x16x32_bf16 v[20:23], v[252:255], v[228:231], v[20:23]
	v_mfma_f32_16x16x32_bf16 v[16:19], v[116:119], v[228:231], v[16:19]
	v_mfma_f32_16x16x32_bf16 v[8:11], v[244:247], v[232:235], v[8:11]
	v_mfma_f32_16x16x32_bf16 v[4:7], v[248:251], v[232:235], v[4:7]
	v_mfma_f32_16x16x32_bf16 v[12:15], v[252:255], v[232:235], v[12:15]
	v_mfma_f32_16x16x32_bf16 v[0:3], v[116:119], v[232:235], v[0:3]
	s_waitcnt lgkmcnt(0)
	v_mfma_f32_16x16x32_bf16 v[92:95], v[166:169], v[134:137], v[92:95]
	s_waitcnt vmcnt(0)
	s_barrier
	v_mfma_f32_16x16x32_bf16 v[88:91], v[200:203], v[134:137], v[88:91]
	s_cmp_eq_u32 s35, 0xf000
	s_cselect_b32 s38, s37, s36
	v_mfma_f32_16x16x32_bf16 v[84:87], v[204:207], v[134:137], v[84:87]
	v_add_u32_e32 v170, s38, v170
	v_add_u32_e32 v172, s38, v172
	s_add_u32 s35, s35, s38
	v_mfma_f32_16x16x32_bf16 v[80:83], v[208:211], v[134:137], v[80:83]
	ds_read_b128 v[212:215], v170
	ds_read_b128 v[216:219], v170 offset:1024
	ds_read_b128 v[220:223], v170 offset:2048
	ds_read_b128 v[224:227], v170 offset:3072
	ds_read_b128 v[228:231], v170 offset:4096
	ds_read_b128 v[232:235], v170 offset:5120
	v_mfma_f32_16x16x32_bf16 v[76:79], v[166:169], v[138:141], v[76:79]
	v_mfma_f32_16x16x32_bf16 v[72:75], v[200:203], v[138:141], v[72:75]
	v_mfma_f32_16x16x32_bf16 v[68:71], v[204:207], v[138:141], v[68:71]
	ds_read_b128 v[244:247], v172 offset:12288
	ds_read_b128 v[248:251], v172 offset:13312
	ds_read_b128 v[252:255], v172 offset:14336
	ds_read_b128 v[116:119], v172 offset:15360
	v_mfma_f32_16x16x32_bf16 v[64:67], v[208:211], v[138:141], v[64:67]
	v_mfma_f32_16x16x32_bf16 v[60:63], v[166:169], v[150:153], v[60:63]
	v_mfma_f32_16x16x32_bf16 v[56:59], v[200:203], v[150:153], v[56:59]
	v_mfma_f32_16x16x32_bf16 v[52:55], v[204:207], v[150:153], v[52:55]
	v_mfma_f32_16x16x32_bf16 v[48:51], v[208:211], v[150:153], v[48:51]
	v_mfma_f32_16x16x32_bf16 v[44:47], v[166:169], v[154:157], v[44:47]
	v_mfma_f32_16x16x32_bf16 v[40:43], v[200:203], v[154:157], v[40:43]
	v_mfma_f32_16x16x32_bf16 v[36:39], v[204:207], v[154:157], v[36:39]
	v_mfma_f32_16x16x32_bf16 v[32:35], v[208:211], v[154:157], v[32:35]
	v_mfma_f32_16x16x32_bf16 v[28:31], v[166:169], v[158:161], v[28:31]
	v_mfma_f32_16x16x32_bf16 v[24:27], v[200:203], v[158:161], v[24:27]
	v_mfma_f32_16x16x32_bf16 v[20:23], v[204:207], v[158:161], v[20:23]
	v_mfma_f32_16x16x32_bf16 v[16:19], v[208:211], v[158:161], v[16:19]
	v_mfma_f32_16x16x32_bf16 v[8:11], v[166:169], v[162:165], v[8:11]
	v_mfma_f32_16x16x32_bf16 v[4:7], v[200:203], v[162:165], v[4:7]
	v_mfma_f32_16x16x32_bf16 v[12:15], v[204:207], v[162:165], v[12:15]
	v_mfma_f32_16x16x32_bf16 v[0:3], v[208:211], v[162:165], v[0:3]
	s_waitcnt lgkmcnt(0)
	v_mfma_f32_16x16x32_bf16 v[92:95], v[244:247], v[212:215], v[92:95]
	v_mfma_f32_16x16x32_bf16 v[88:91], v[248:251], v[212:215], v[88:91]
	v_mfma_f32_16x16x32_bf16 v[84:87], v[252:255], v[212:215], v[84:87]
	v_mfma_f32_16x16x32_bf16 v[80:83], v[116:119], v[212:215], v[80:83]
	v_mfma_f32_16x16x32_bf16 v[76:79], v[244:247], v[216:219], v[76:79]
	v_mfma_f32_16x16x32_bf16 v[72:75], v[248:251], v[216:219], v[72:75]
	v_mfma_f32_16x16x32_bf16 v[68:71], v[252:255], v[216:219], v[68:71]
	v_mfma_f32_16x16x32_bf16 v[64:67], v[116:119], v[216:219], v[64:67]
	v_mfma_f32_16x16x32_bf16 v[60:63], v[244:247], v[220:223], v[60:63]
	v_mfma_f32_16x16x32_bf16 v[56:59], v[248:251], v[220:223], v[56:59]
	v_mfma_f32_16x16x32_bf16 v[52:55], v[252:255], v[220:223], v[52:55]
	v_mfma_f32_16x16x32_bf16 v[48:51], v[116:119], v[220:223], v[48:51]
	v_mfma_f32_16x16x32_bf16 v[44:47], v[244:247], v[224:227], v[44:47]
	v_mfma_f32_16x16x32_bf16 v[40:43], v[248:251], v[224:227], v[40:43]
	v_mfma_f32_16x16x32_bf16 v[36:39], v[252:255], v[224:227], v[36:39]
	v_mfma_f32_16x16x32_bf16 v[32:35], v[116:119], v[224:227], v[32:35]
	v_mfma_f32_16x16x32_bf16 v[28:31], v[244:247], v[228:231], v[28:31]
	v_mfma_f32_16x16x32_bf16 v[24:27], v[248:251], v[228:231], v[24:27]
	v_mfma_f32_16x16x32_bf16 v[20:23], v[252:255], v[228:231], v[20:23]
	v_mfma_f32_16x16x32_bf16 v[16:19], v[116:119], v[228:231], v[16:19]
	v_mfma_f32_16x16x32_bf16 v[8:11], v[244:247], v[232:235], v[8:11]
	v_mfma_f32_16x16x32_bf16 v[4:7], v[248:251], v[232:235], v[4:7]
	v_mfma_f32_16x16x32_bf16 v[12:15], v[252:255], v[232:235], v[12:15]
	v_mfma_f32_16x16x32_bf16 v[0:3], v[116:119], v[232:235], v[0:3]
	s_barrier
	v_mov_b32_e32 v170, s46
	v_mov_b32_e32 v172, s47
	ds_write_b32 v183, v170
	ds_write_b32 v184, v172
	s_waitcnt lgkmcnt(0)
	s_add_i32 s9, s9, s51
	v_readlane_b32 s10, v241, 9
	s_cmp_eq_u32 s10, 7
	s_cbranch_scc0 .Lout_epi_ln
	v_readlane_b32 s10, v243, 21
	v_readlane_b32 s11, v243, 22
	v_readlane_b32 s12, v242, 29
	v_readlane_b32 s13, v242, 30
	v_readlane_b32 s14, v243, 11
	v_readlane_b32 s15, v243, 12
	s_mov_b32 s6, 0x3fd744fd
	v_add_u32_e32 v236, s0, v145
	v_or_b32_e32 v254, s4, v146
	v_mov_b32_e32 v255, 0
	v_or_b32_e32 v237, v236, v133
	v_lshlrev_b64 v[254:255], 2, v[254:255]
	s_nop 0
	v_lshl_add_u64 v[248:249], s[10:11], 0, v[254:255]
	v_lshl_add_u64 v[250:251], s[12:13], 0, v[254:255]
	v_lshl_add_u64 v[252:253], s[14:15], 0, v[254:255]
	s_mov_b64 s[10:11], 0x2000
	v_mov_b32_e32 v255, 0
	v_lshl_add_u64 v[252:253], v[252:253], 0, s[10:11]
	v_readlane_b32 s10, v243, 21
	v_readlane_b32 s11, v243, 22
	v_readlane_b32 s12, v243, 23
	v_readlane_b32 s13, v243, 24
	s_sub_u32 s12, s12, s10
	s_subb_u32 s13, s13, s11
	s_sub_u32 s12, s12, 0x1000000
	s_subb_u32 s13, s13, 0
	v_add_u32_e32 v254, 0, v237
	v_add_u32_e32 v236, 0xfffff000, v254
	v_cmp_lt_i32_e32 vcc, 0xfff, v254
	v_lshrrev_b32_e32 v236, 10, v236
	v_lshlrev_b32_e32 v254, 12, v254
	v_add_u32_e32 v236, 1, v236
	v_cndmask_b32_e32 v236, 0, v236, vcc
	v_lshl_add_u64 v[224:225], v[254:255], 0, v[248:249]
	v_lshl_add_u64 v[228:229], v[254:255], 0, v[250:251]
	v_add_u32_e32 v236, s8, v236
	v_mad_i64_i32 v[232:233], s[0:1], v236, s33, v[252:253]
	v_mov_b32_e32 v236, s12
	v_mov_b32_e32 v254, s13
	v_cndmask_b32_e32 v236, 0, v236, vcc
	v_cndmask_b32_e32 v254, 0, v254, vcc
	v_add_co_u32_e32 v224, vcc, v224, v236
	s_nop 0
	v_addc_co_u32_e32 v225, vcc, v225, v254, vcc
	v_add_u32_e32 v254, 16, v237
	v_add_u32_e32 v236, 0xfffff000, v254
	v_cmp_lt_i32_e32 vcc, 0xfff, v254
	v_lshrrev_b32_e32 v236, 10, v236
	v_lshlrev_b32_e32 v254, 12, v254
	v_add_u32_e32 v236, 1, v236
	v_cndmask_b32_e32 v236, 0, v236, vcc
	v_lshl_add_u64 v[226:227], v[254:255], 0, v[248:249]
	v_lshl_add_u64 v[230:231], v[254:255], 0, v[250:251]
	v_add_u32_e32 v236, s8, v236
	v_mad_i64_i32 v[234:235], s[0:1], v236, s33, v[252:253]
	v_mov_b32_e32 v236, s12
	v_mov_b32_e32 v254, s13
	v_cndmask_b32_e32 v236, 0, v236, vcc
	v_cndmask_b32_e32 v254, 0, v254, vcc
	v_add_co_u32_e32 v226, vcc, v226, v236
	s_nop 0
	v_addc_co_u32_e32 v227, vcc, v227, v254, vcc
	global_load_dwordx4 v[154:157], v[224:225], off
	global_load_dwordx4 v[116:119], v[232:233], off
	global_load_dwordx4 v[158:161], v[224:225], off offset:64
	global_load_dwordx4 v[120:123], v[232:233], off offset:64
	global_load_dwordx4 v[162:165], v[224:225], off offset:128
	global_load_dwordx4 v[124:127], v[232:233], off offset:128
	global_load_dwordx4 v[166:169], v[224:225], off offset:192
	global_load_dwordx4 v[134:137], v[232:233], off offset:192
	global_load_dwordx4 v[208:211], v[226:227], off
	global_load_dwordx4 v[138:141], v[234:235], off
	global_load_dwordx4 v[212:215], v[226:227], off offset:64
	global_load_dwordx4 v[200:203], v[234:235], off offset:64
	global_load_dwordx4 v[216:219], v[226:227], off offset:128
	global_load_dwordx4 v[204:207], v[234:235], off offset:128
	global_load_dwordx4 v[220:223], v[226:227], off offset:192
	global_load_dwordx4 v[244:247], v[234:235], off offset:192
	s_waitcnt vmcnt(0)
	v_pk_mul_f32 v[92:93], v[92:93], v[116:117]
	v_pk_mul_f32 v[94:95], v[94:95], v[118:119]
	v_pk_fma_f32 v[92:93], v[154:155], s[6:7], v[92:93] op_sel_hi:[1,0,1]
	v_pk_fma_f32 v[94:95], v[156:157], s[6:7], v[94:95] op_sel_hi:[1,0,1]
	global_store_dwordx4 v[228:229], v[92:95], off
	v_pk_mul_f32 v[88:89], v[88:89], v[120:121]
	v_pk_mul_f32 v[90:91], v[90:91], v[122:123]
	v_pk_fma_f32 v[88:89], v[158:159], s[6:7], v[88:89] op_sel_hi:[1,0,1]
	v_pk_fma_f32 v[90:91], v[160:161], s[6:7], v[90:91] op_sel_hi:[1,0,1]
	global_store_dwordx4 v[228:229], v[88:91], off offset:64
	v_pk_mul_f32 v[84:85], v[84:85], v[124:125]
	v_pk_mul_f32 v[86:87], v[86:87], v[126:127]
	v_pk_fma_f32 v[84:85], v[162:163], s[6:7], v[84:85] op_sel_hi:[1,0,1]
	v_pk_fma_f32 v[86:87], v[164:165], s[6:7], v[86:87] op_sel_hi:[1,0,1]
	global_store_dwordx4 v[228:229], v[84:87], off offset:128
	v_pk_mul_f32 v[80:81], v[80:81], v[134:135]
	v_pk_mul_f32 v[82:83], v[82:83], v[136:137]
	v_pk_fma_f32 v[80:81], v[166:167], s[6:7], v[80:81] op_sel_hi:[1,0,1]
	v_pk_fma_f32 v[82:83], v[168:169], s[6:7], v[82:83] op_sel_hi:[1,0,1]
	global_store_dwordx4 v[228:229], v[80:83], off offset:192
	v_pk_mul_f32 v[76:77], v[76:77], v[138:139]
	v_pk_mul_f32 v[78:79], v[78:79], v[140:141]
	v_pk_fma_f32 v[76:77], v[208:209], s[6:7], v[76:77] op_sel_hi:[1,0,1]
	v_pk_fma_f32 v[78:79], v[210:211], s[6:7], v[78:79] op_sel_hi:[1,0,1]
	global_store_dwordx4 v[230:231], v[76:79], off
	v_pk_mul_f32 v[72:73], v[72:73], v[200:201]
	v_pk_mul_f32 v[74:75], v[74:75], v[202:203]
	v_pk_fma_f32 v[72:73], v[212:213], s[6:7], v[72:73] op_sel_hi:[1,0,1]
	v_pk_fma_f32 v[74:75], v[214:215], s[6:7], v[74:75] op_sel_hi:[1,0,1]
	global_store_dwordx4 v[230:231], v[72:75], off offset:64
	v_pk_mul_f32 v[68:69], v[68:69], v[204:205]
	v_pk_mul_f32 v[70:71], v[70:71], v[206:207]
	v_pk_fma_f32 v[68:69], v[216:217], s[6:7], v[68:69] op_sel_hi:[1,0,1]
	v_pk_fma_f32 v[70:71], v[218:219], s[6:7], v[70:71] op_sel_hi:[1,0,1]
	global_store_dwordx4 v[230:231], v[68:71], off offset:128
	v_pk_mul_f32 v[64:65], v[64:65], v[244:245]
	v_pk_mul_f32 v[66:67], v[66:67], v[246:247]
	v_pk_fma_f32 v[64:65], v[220:221], s[6:7], v[64:65] op_sel_hi:[1,0,1]
	v_pk_fma_f32 v[66:67], v[222:223], s[6:7], v[66:67] op_sel_hi:[1,0,1]
	global_store_dwordx4 v[230:231], v[64:67], off offset:192
	v_add_u32_e32 v254, 32, v237
	v_add_u32_e32 v236, 0xfffff000, v254
	v_cmp_lt_i32_e32 vcc, 0xfff, v254
	v_lshrrev_b32_e32 v236, 10, v236
	v_lshlrev_b32_e32 v254, 12, v254
	v_add_u32_e32 v236, 1, v236
	v_cndmask_b32_e32 v236, 0, v236, vcc
	v_lshl_add_u64 v[224:225], v[254:255], 0, v[248:249]
	v_lshl_add_u64 v[228:229], v[254:255], 0, v[250:251]
	v_add_u32_e32 v236, s8, v236
	v_mad_i64_i32 v[232:233], s[0:1], v236, s33, v[252:253]
	v_mov_b32_e32 v236, s12
	v_mov_b32_e32 v254, s13
	v_cndmask_b32_e32 v236, 0, v236, vcc
	v_cndmask_b32_e32 v254, 0, v254, vcc
	v_add_co_u32_e32 v224, vcc, v224, v236
	s_nop 0
	v_addc_co_u32_e32 v225, vcc, v225, v254, vcc
	v_add_u32_e32 v254, 48, v237
	v_add_u32_e32 v236, 0xfffff000, v254
	v_cmp_lt_i32_e32 vcc, 0xfff, v254
	v_lshrrev_b32_e32 v236, 10, v236
	v_lshlrev_b32_e32 v254, 12, v254
	v_add_u32_e32 v236, 1, v236
	v_cndmask_b32_e32 v236, 0, v236, vcc
	v_lshl_add_u64 v[226:227], v[254:255], 0, v[248:249]
	v_lshl_add_u64 v[230:231], v[254:255], 0, v[250:251]
	v_add_u32_e32 v236, s8, v236
	v_mad_i64_i32 v[234:235], s[0:1], v236, s33, v[252:253]
	v_mov_b32_e32 v236, s12
	v_mov_b32_e32 v254, s13
	v_cndmask_b32_e32 v236, 0, v236, vcc
	v_cndmask_b32_e32 v254, 0, v254, vcc
	v_add_co_u32_e32 v226, vcc, v226, v236
	s_nop 0
	v_addc_co_u32_e32 v227, vcc, v227, v254, vcc
	global_load_dwordx4 v[154:157], v[224:225], off
	global_load_dwordx4 v[116:119], v[232:233], off
	global_load_dwordx4 v[158:161], v[224:225], off offset:64
	global_load_dwordx4 v[120:123], v[232:233], off offset:64
	global_load_dwordx4 v[162:165], v[224:225], off offset:128
	global_load_dwordx4 v[124:127], v[232:233], off offset:128
	global_load_dwordx4 v[166:169], v[224:225], off offset:192
	global_load_dwordx4 v[134:137], v[232:233], off offset:192
	global_load_dwordx4 v[208:211], v[226:227], off
	global_load_dwordx4 v[138:141], v[234:235], off
	global_load_dwordx4 v[212:215], v[226:227], off offset:64
	global_load_dwordx4 v[200:203], v[234:235], off offset:64
	global_load_dwordx4 v[216:219], v[226:227], off offset:128
	global_load_dwordx4 v[204:207], v[234:235], off offset:128
	global_load_dwordx4 v[220:223], v[226:227], off offset:192
	global_load_dwordx4 v[244:247], v[234:235], off offset:192
	s_waitcnt vmcnt(0)
	v_pk_mul_f32 v[60:61], v[60:61], v[116:117]
	v_pk_mul_f32 v[62:63], v[62:63], v[118:119]
	v_pk_fma_f32 v[60:61], v[154:155], s[6:7], v[60:61] op_sel_hi:[1,0,1]
	v_pk_fma_f32 v[62:63], v[156:157], s[6:7], v[62:63] op_sel_hi:[1,0,1]
	global_store_dwordx4 v[228:229], v[60:63], off
	v_pk_mul_f32 v[56:57], v[56:57], v[120:121]
	v_pk_mul_f32 v[58:59], v[58:59], v[122:123]
	v_pk_fma_f32 v[56:57], v[158:159], s[6:7], v[56:57] op_sel_hi:[1,0,1]
	v_pk_fma_f32 v[58:59], v[160:161], s[6:7], v[58:59] op_sel_hi:[1,0,1]
	global_store_dwordx4 v[228:229], v[56:59], off offset:64
	v_pk_mul_f32 v[52:53], v[52:53], v[124:125]
	v_pk_mul_f32 v[54:55], v[54:55], v[126:127]
	v_pk_fma_f32 v[52:53], v[162:163], s[6:7], v[52:53] op_sel_hi:[1,0,1]
	v_pk_fma_f32 v[54:55], v[164:165], s[6:7], v[54:55] op_sel_hi:[1,0,1]
	global_store_dwordx4 v[228:229], v[52:55], off offset:128
	v_pk_mul_f32 v[48:49], v[48:49], v[134:135]
	v_pk_mul_f32 v[50:51], v[50:51], v[136:137]
	v_pk_fma_f32 v[48:49], v[166:167], s[6:7], v[48:49] op_sel_hi:[1,0,1]
	v_pk_fma_f32 v[50:51], v[168:169], s[6:7], v[50:51] op_sel_hi:[1,0,1]
	global_store_dwordx4 v[228:229], v[48:51], off offset:192
	v_pk_mul_f32 v[44:45], v[44:45], v[138:139]
	v_pk_mul_f32 v[46:47], v[46:47], v[140:141]
	v_pk_fma_f32 v[44:45], v[208:209], s[6:7], v[44:45] op_sel_hi:[1,0,1]
	v_pk_fma_f32 v[46:47], v[210:211], s[6:7], v[46:47] op_sel_hi:[1,0,1]
	global_store_dwordx4 v[230:231], v[44:47], off
	v_pk_mul_f32 v[40:41], v[40:41], v[200:201]
	v_pk_mul_f32 v[42:43], v[42:43], v[202:203]
	v_pk_fma_f32 v[40:41], v[212:213], s[6:7], v[40:41] op_sel_hi:[1,0,1]
	v_pk_fma_f32 v[42:43], v[214:215], s[6:7], v[42:43] op_sel_hi:[1,0,1]
	global_store_dwordx4 v[230:231], v[40:43], off offset:64
	v_pk_mul_f32 v[36:37], v[36:37], v[204:205]
	v_pk_mul_f32 v[38:39], v[38:39], v[206:207]
	v_pk_fma_f32 v[36:37], v[216:217], s[6:7], v[36:37] op_sel_hi:[1,0,1]
	v_pk_fma_f32 v[38:39], v[218:219], s[6:7], v[38:39] op_sel_hi:[1,0,1]
	global_store_dwordx4 v[230:231], v[36:39], off offset:128
	v_pk_mul_f32 v[32:33], v[32:33], v[244:245]
	v_pk_mul_f32 v[34:35], v[34:35], v[246:247]
	v_pk_fma_f32 v[32:33], v[220:221], s[6:7], v[32:33] op_sel_hi:[1,0,1]
	v_pk_fma_f32 v[34:35], v[222:223], s[6:7], v[34:35] op_sel_hi:[1,0,1]
	global_store_dwordx4 v[230:231], v[32:35], off offset:192
	v_add_u32_e32 v254, 64, v237
	v_add_u32_e32 v236, 0xfffff000, v254
	v_cmp_lt_i32_e32 vcc, 0xfff, v254
	v_lshrrev_b32_e32 v236, 10, v236
	v_lshlrev_b32_e32 v254, 12, v254
	v_add_u32_e32 v236, 1, v236
	v_cndmask_b32_e32 v236, 0, v236, vcc
	v_lshl_add_u64 v[224:225], v[254:255], 0, v[248:249]
	v_lshl_add_u64 v[228:229], v[254:255], 0, v[250:251]
	v_add_u32_e32 v236, s8, v236
	v_mad_i64_i32 v[232:233], s[0:1], v236, s33, v[252:253]
	v_mov_b32_e32 v236, s12
	v_mov_b32_e32 v254, s13
	v_cndmask_b32_e32 v236, 0, v236, vcc
	v_cndmask_b32_e32 v254, 0, v254, vcc
	v_add_co_u32_e32 v224, vcc, v224, v236
	s_nop 0
	v_addc_co_u32_e32 v225, vcc, v225, v254, vcc
	v_add_u32_e32 v254, 80, v237
	v_add_u32_e32 v236, 0xfffff000, v254
	v_cmp_lt_i32_e32 vcc, 0xfff, v254
	v_lshrrev_b32_e32 v236, 10, v236
	v_lshlrev_b32_e32 v254, 12, v254
	v_add_u32_e32 v236, 1, v236
	v_cndmask_b32_e32 v236, 0, v236, vcc
	v_lshl_add_u64 v[226:227], v[254:255], 0, v[248:249]
	v_lshl_add_u64 v[230:231], v[254:255], 0, v[250:251]
	v_add_u32_e32 v236, s8, v236
	v_mad_i64_i32 v[234:235], s[0:1], v236, s33, v[252:253]
	v_mov_b32_e32 v236, s12
	v_mov_b32_e32 v254, s13
	v_cndmask_b32_e32 v236, 0, v236, vcc
	v_cndmask_b32_e32 v254, 0, v254, vcc
	v_add_co_u32_e32 v226, vcc, v226, v236
	s_nop 0
	v_addc_co_u32_e32 v227, vcc, v227, v254, vcc
	global_load_dwordx4 v[154:157], v[224:225], off
	global_load_dwordx4 v[116:119], v[232:233], off
	global_load_dwordx4 v[158:161], v[224:225], off offset:64
	global_load_dwordx4 v[120:123], v[232:233], off offset:64
	global_load_dwordx4 v[162:165], v[224:225], off offset:128
	global_load_dwordx4 v[124:127], v[232:233], off offset:128
	global_load_dwordx4 v[166:169], v[224:225], off offset:192
	global_load_dwordx4 v[134:137], v[232:233], off offset:192
	global_load_dwordx4 v[208:211], v[226:227], off
	global_load_dwordx4 v[138:141], v[234:235], off
	global_load_dwordx4 v[212:215], v[226:227], off offset:64
	global_load_dwordx4 v[200:203], v[234:235], off offset:64
	global_load_dwordx4 v[216:219], v[226:227], off offset:128
	global_load_dwordx4 v[204:207], v[234:235], off offset:128
	global_load_dwordx4 v[220:223], v[226:227], off offset:192
	global_load_dwordx4 v[244:247], v[234:235], off offset:192
	s_waitcnt vmcnt(0)
	v_pk_mul_f32 v[28:29], v[28:29], v[116:117]
	v_pk_mul_f32 v[30:31], v[30:31], v[118:119]
	v_pk_fma_f32 v[28:29], v[154:155], s[6:7], v[28:29] op_sel_hi:[1,0,1]
	v_pk_fma_f32 v[30:31], v[156:157], s[6:7], v[30:31] op_sel_hi:[1,0,1]
	global_store_dwordx4 v[228:229], v[28:31], off
	v_pk_mul_f32 v[24:25], v[24:25], v[120:121]
	v_pk_mul_f32 v[26:27], v[26:27], v[122:123]
	v_pk_fma_f32 v[24:25], v[158:159], s[6:7], v[24:25] op_sel_hi:[1,0,1]
	v_pk_fma_f32 v[26:27], v[160:161], s[6:7], v[26:27] op_sel_hi:[1,0,1]
	global_store_dwordx4 v[228:229], v[24:27], off offset:64
	v_pk_mul_f32 v[20:21], v[20:21], v[124:125]
	v_pk_mul_f32 v[22:23], v[22:23], v[126:127]
	v_pk_fma_f32 v[20:21], v[162:163], s[6:7], v[20:21] op_sel_hi:[1,0,1]
	v_pk_fma_f32 v[22:23], v[164:165], s[6:7], v[22:23] op_sel_hi:[1,0,1]
	global_store_dwordx4 v[228:229], v[20:23], off offset:128
	v_pk_mul_f32 v[16:17], v[16:17], v[134:135]
	v_pk_mul_f32 v[18:19], v[18:19], v[136:137]
	v_pk_fma_f32 v[16:17], v[166:167], s[6:7], v[16:17] op_sel_hi:[1,0,1]
	v_pk_fma_f32 v[18:19], v[168:169], s[6:7], v[18:19] op_sel_hi:[1,0,1]
	global_store_dwordx4 v[228:229], v[16:19], off offset:192
	v_pk_mul_f32 v[8:9], v[8:9], v[138:139]
	v_pk_mul_f32 v[10:11], v[10:11], v[140:141]
	v_pk_fma_f32 v[8:9], v[208:209], s[6:7], v[8:9] op_sel_hi:[1,0,1]
	v_pk_fma_f32 v[10:11], v[210:211], s[6:7], v[10:11] op_sel_hi:[1,0,1]
	global_store_dwordx4 v[230:231], v[8:11], off
	v_pk_mul_f32 v[4:5], v[4:5], v[200:201]
	v_pk_mul_f32 v[6:7], v[6:7], v[202:203]
	v_pk_fma_f32 v[4:5], v[212:213], s[6:7], v[4:5] op_sel_hi:[1,0,1]
	v_pk_fma_f32 v[6:7], v[214:215], s[6:7], v[6:7] op_sel_hi:[1,0,1]
	global_store_dwordx4 v[230:231], v[4:7], off offset:64
	v_pk_mul_f32 v[12:13], v[12:13], v[204:205]
	v_pk_mul_f32 v[14:15], v[14:15], v[206:207]
	v_pk_fma_f32 v[12:13], v[216:217], s[6:7], v[12:13] op_sel_hi:[1,0,1]
	v_pk_fma_f32 v[14:15], v[218:219], s[6:7], v[14:15] op_sel_hi:[1,0,1]
	global_store_dwordx4 v[230:231], v[12:15], off offset:128
	v_pk_mul_f32 v[0:1], v[0:1], v[244:245]
	v_pk_mul_f32 v[2:3], v[2:3], v[246:247]
	v_pk_fma_f32 v[0:1], v[220:221], s[6:7], v[0:1] op_sel_hi:[1,0,1]
	v_pk_fma_f32 v[2:3], v[222:223], s[6:7], v[2:3] op_sel_hi:[1,0,1]
	global_store_dwordx4 v[230:231], v[0:3], off offset:192
	s_branch .Lout_epi_done
